# up-GEMM epilogue: conv bias folded into the first FMA of 45 tap chains (fast path), DPP neighbour moves use bound_ctrl instead of a preceding zero move
# speedup vs baseline: 1.0090x; 1.0022x over previous
;     __device__ __forceinline__ void operator()(const f32x4 (&acc)[2][2][4][2], const Unit& u, int wr, int wc, int fr, int fq) const {
;         const int grow0 = 252 * u.pm + 126 * wr - 1 + 8 * fr;
;         const int cg0 = 128 * u.pn + 32 * wc + 8 * fq;
;         float rs[8]; bool pz[8], nz[8];
; #pragma unroll
;         for (int i = 0; i < 8; ++i) { const int t = T0 + grow0 + i; const int tc = t < 0 ? 0 : (t > MTOK - 1 ? MTOK - 1 : t); rs[i] = rstd[tc];
;             pz[i] = ((t & 8191) == 0) && (t != 24576); nz[i] = (((t + 1) & 8191) == 0) && (t + 1 != 24576); }
; #pragma unroll
;         for (int n = 0; n < 2; ++n) {
;             float res[8][4];
; #pragma unroll
;             for (int j = 0; j < 4; ++j) {
;                 const int cg = cg0 + 4 * n + j;
;                 const float gw0 = cw[cg], gw1 = cw[NUP + cg], gw2 = cw[2 * NUP + cg], gb = cb[cg];
;                 const float vw0 = cw[DFF + cg], vw1 = cw[NUP + DFF + cg], vw2 = cw[2 * NUP + DFF + cg], vb = cb[DFF + cg];
;                 float xg[8], xv[8];
; #pragma unroll
;                 for (int i = 0; i < 8; ++i) { xg[i] = acc[i >> 2][0][i & 3][n][j] * rs[i]; xv[i] = acc[i >> 2][1][i & 3][n][j] * rs[i]; }
;                 const float gp = __builtin_bit_cast(float, __builtin_amdgcn_update_dpp(0, __builtin_bit_cast(int, xg[7]), 0x111, 0xf, 0xf, false));
;                 const float gn = __builtin_bit_cast(float, __builtin_amdgcn_update_dpp(0, __builtin_bit_cast(int, xg[0]), 0x101, 0xf, 0xf, false));
;                 const float vp = __builtin_bit_cast(float, __builtin_amdgcn_update_dpp(0, __builtin_bit_cast(int, xv[7]), 0x111, 0xf, 0xf, false));
;                 const float vn = __builtin_bit_cast(float, __builtin_amdgcn_update_dpp(0, __builtin_bit_cast(int, xv[0]), 0x101, 0xf, 0xf, false));
.LBB0_598:
	s_mul_i32 s10, s22, 0xfc
	v_add_u32_e32 v189, s10, v252
	v_add_u32_e32 v106, s48, v189
	v_add_u32_e32 v107, 8, v106
	v_and_b32_e32 v107, 0x1fff, v107
	v_cmp_gt_u32_e32 vcc, 9, v107
	s_cbranch_vccz .Lupf_start
	v_add_u32_e32 v195, 7, v106
	v_med3_i32 v107, v106, 0, s65
	v_add_u32_e32 v203, 1, v106
	v_add_u32_e32 v191, 2, v106
	v_add_u32_e32 v193, 3, v106
	v_add_u32_e32 v201, 4, v106
	v_add_u32_e32 v199, 5, v106
	v_add_u32_e32 v197, 6, v106
	v_med3_i32 v106, v195, 0, s65
	v_lshl_or_b32 v186, s12, 7, v253
	v_lshlrev_b32_e32 v107, 2, v107
	v_med3_i32 v108, v203, 0, s65
	v_lshlrev_b32_e32 v106, 2, v106
	v_ashrrev_i32_e32 v187, 31, v186
	v_lshlrev_b32_e32 v108, 2, v108
	global_load_dword v198, v107, s[42:43]
	global_load_dword v200, v108, s[42:43]
	global_load_dword v202, v106, s[42:43]
	v_lshlrev_b64 v[106:107], 2, v[186:187]
	v_lshl_add_u64 v[206:207], s[52:53], 0, v[106:107]
	s_movk_i32 s10, 0x5000
	v_add_co_u32_e32 v208, vcc, s10, v206
	v_med3_i32 v109, v191, 0, s65
	s_nop 0
	v_addc_co_u32_e32 v209, vcc, 0, v207, vcc
	v_add_co_u32_e32 v210, vcc, s84, v206
	s_mov_b32 s10, 0xd000
	s_nop 0
	v_addc_co_u32_e32 v211, vcc, 0, v207, vcc
	v_add_co_u32_e32 v212, vcc, s66, v206
	v_lshlrev_b32_e32 v188, 2, v109
	s_nop 0
	v_addc_co_u32_e32 v213, vcc, 0, v207, vcc
	v_add_co_u32_e32 v214, vcc, s45, v206
	v_med3_i32 v109, v193, 0, s65
	s_nop 0
	v_addc_co_u32_e32 v215, vcc, 0, v207, vcc
	v_add_co_u32_e32 v216, vcc, s10, v206
	v_lshlrev_b32_e32 v190, 2, v109
	v_med3_i32 v109, v201, 0, s65
	v_lshl_add_u64 v[204:205], s[54:55], 0, v[106:107]
	v_addc_co_u32_e32 v217, vcc, 0, v207, vcc
	v_lshlrev_b32_e32 v192, 2, v109
	v_med3_i32 v109, v199, 0, s65
	v_add_co_u32_e32 v218, vcc, s66, v204
	v_lshlrev_b32_e32 v220, 2, v109
	v_med3_i32 v109, v197, 0, s65
	v_addc_co_u32_e32 v219, vcc, 0, v205, vcc
	v_lshlrev_b32_e32 v221, 2, v109
	global_load_dwordx4 v[106:109], v[206:207], off
	global_load_dwordx4 v[122:125], v[208:209], off offset:2048
	global_load_dwordx4 v[110:113], v[210:211], off
	global_load_dwordx4 v[118:121], v[204:205], off
	global_load_dwordx4 v[114:117], v[212:213], off offset:3072
	global_load_dwordx4 v[126:129], v[214:215], off offset:1024
	global_load_dwordx4 v[130:133], v[216:217], off offset:3072
	global_load_dwordx4 v[138:141], v[218:219], off offset:3072
	global_load_dword v196, v188, s[42:43]
	global_load_dword v194, v190, s[42:43]
	s_nop 0
	global_load_dword v192, v192, s[42:43]
	s_nop 0
	global_load_dword v190, v220, s[42:43]
	global_load_dword v188, v221, s[42:43]
	v_and_b32_e32 v220, 0x1fff, v203
	v_cmp_ne_u32_e32 vcc, s67, v203
	v_cmp_eq_u32_e64 s[10:11], 0, v220
	s_and_b64 s[94:95], vcc, s[10:11]
	v_cmp_gt_i32_e32 vcc, s47, v189
	s_and_b64 s[88:89], s[4:5], vcc
	s_waitcnt vmcnt(0)
	v_pk_mul_f32 v[228:229], v[158:159], v[198:199] op_sel_hi:[1,0]
	v_pk_mul_f32 v[222:223], v[154:155], v[200:201] op_sel_hi:[1,0]
	v_pk_mul_f32 v[158:159], v[142:143], v[202:203] op_sel_hi:[1,0]
	v_pk_mul_f32 v[142:143], v[134:135], v[202:203] op_sel_hi:[1,0]
	v_pk_mul_f32 v[220:221], v[146:147], v[200:201] op_sel_hi:[1,0]
	v_pk_mul_f32 v[230:231], v[150:151], v[198:199] op_sel_hi:[1,0]
	v_pk_mul_f32 v[144:145], v[144:145], v[202:203] op_sel_hi:[1,0]
	v_pk_mul_f32 v[134:135], v[136:137], v[202:203] op_sel_hi:[1,0]
	v_pk_mul_f32 v[150:151], v[148:149], v[200:201] op_sel_hi:[1,0]
	v_pk_mul_f32 v[224:225], v[160:161], v[198:199] op_sel_hi:[1,0]
	v_pk_mul_f32 v[226:227], v[152:153], v[198:199] op_sel_hi:[1,0]
	v_mov_b32_dpp v234, v158 row_shr:1 row_mask:0xf bank_mask:0xf bound_ctrl:1
	v_mov_b32_dpp v232, v142 row_shr:1 row_mask:0xf bank_mask:0xf bound_ctrl:1
	v_mov_b32_dpp v235, v159 row_shr:1 row_mask:0xf bank_mask:0xf bound_ctrl:1
	v_mov_b32_dpp v233, v143 row_shr:1 row_mask:0xf bank_mask:0xf bound_ctrl:1
	v_mov_b32_dpp v154, v228 row_shl:1 row_mask:0xf bank_mask:0xf bound_ctrl:1
	v_mov_b32_dpp v146, v230 row_shl:1 row_mask:0xf bank_mask:0xf bound_ctrl:1
	v_mov_b32_dpp v155, v229 row_shl:1 row_mask:0xf bank_mask:0xf bound_ctrl:1
	v_mov_b32_dpp v147, v231 row_shl:1 row_mask:0xf bank_mask:0xf bound_ctrl:1
	v_mov_b32_dpp v238, v144 row_shr:1 row_mask:0xf bank_mask:0xf bound_ctrl:1
	v_mov_b32_dpp v236, v134 row_shr:1 row_mask:0xf bank_mask:0xf bound_ctrl:1
	v_mov_b32_dpp v239, v145 row_shr:1 row_mask:0xf bank_mask:0xf bound_ctrl:1
	v_mov_b32_dpp v237, v135 row_shr:1 row_mask:0xf bank_mask:0xf bound_ctrl:1
	v_pk_mul_f32 v[156:157], v[156:157], v[200:201] op_sel_hi:[1,0]
	v_mov_b32_dpp v148, v224 row_shl:1 row_mask:0xf bank_mask:0xf bound_ctrl:1
	v_mov_b32_dpp v136, v226 row_shl:1 row_mask:0xf bank_mask:0xf bound_ctrl:1
	v_mov_b32_dpp v149, v225 row_shl:1 row_mask:0xf bank_mask:0xf bound_ctrl:1
	v_mov_b32_dpp v137, v227 row_shl:1 row_mask:0xf bank_mask:0xf bound_ctrl:1
	s_and_saveexec_b64 s[10:11], s[88:89]
	s_cbranch_execz .LBB0_600
;     __device__ __forceinline__ void operator()(const f32x4 (&acc)[2][2][4][2], const Unit& u, int wr, int wc, int fr, int fq) const {
;     ...
;                 for (int i = 0; i < 8; ++i) {
;                     float pg = i > 0 ? xg[i - 1] : gp, ng = i < 7 ? xg[i + 1] : gn, pv = i > 0 ? xv[i - 1] : vp, nv = i < 7 ? xv[i + 1] : vn;
;                     if (pz[i]) { pg = 0.f; pv = 0.f; } if (nz[i]) { ng = 0.f; nv = 0.f; }
;                     const float cgv = gw0 * pg + gw1 * xg[i] + gw2 * ng + gb;
;                     const float cvv = vw0 * pv + vw1 * xv[i] + vw2 * nv + vb;
;                     res[i][j] = gelu_tanh(cgv) * cvv;
;                 }
;             }
; #pragma unroll
;             for (int i = 0; i < 8; ++i) { const int s = 8 * fr + i, grow = grow0 + i;
;                 if (s >= 1 && s <= 126 && grow < HALF_TOK) { u32x2 w; w.x = pk2(res[i][0], res[i][1]); w.y = pk2(res[i][2], res[i][3]); *(u32x2*)(G + (size_t)grow * DFF + cg0 + 4 * n) = w; } }
	v_pk_mul_f32 v[152:153], v[108:109], v[238:239]
	v_cndmask_b32_e64 v161, v157, 0, s[94:95]
	v_pk_fma_f32 v[152:153], v[224:225], v[124:125], v[152:153]
	v_cndmask_b32_e64 v160, v156, 0, s[94:95]
	v_pk_fma_f32 v[152:153], v[160:161], v[112:113], v[152:153]
	v_pk_mul_f32 v[236:237], v[116:117], v[236:237]
	v_pk_add_f32 v[152:153], v[120:121], v[152:153]
	v_pk_fma_f32 v[236:237], v[226:227], v[128:129], v[236:237]
	v_pk_mul_f32 v[160:161], v[152:153], v[152:153]
	v_cndmask_b32_e64 v239, v151, 0, s[94:95]
	v_fmamk_f32 v161, v161, 0xbdd2d3e8, v245
	v_fmamk_f32 v160, v160, 0xbdd2d3e8, v245
	v_cndmask_b32_e64 v238, v150, 0, s[94:95]
	v_pk_mul_f32 v[234:235], v[106:107], v[234:235]
	v_mul_f32_e32 v161, v153, v161
	v_mul_f32_e32 v160, v152, v160
	v_pk_fma_f32 v[236:237], v[238:239], v[132:133], v[236:237]
	v_pk_fma_f32 v[234:235], v[228:229], v[122:123], v[234:235]
	v_cndmask_b32_e64 v239, v223, 0, s[94:95]
	v_cndmask_b32_e64 v238, v222, 0, s[94:95]
	v_exp_f32_e32 v161, v161
	v_exp_f32_e32 v160, v160
	v_pk_fma_f32 v[234:235], v[238:239], v[110:111], v[234:235]
	v_pk_add_f32 v[236:237], v[140:141], v[236:237]
	v_pk_add_f32 v[234:235], v[118:119], v[234:235]
	v_add_f32_e32 v161, 1.0, v161
	v_pk_mul_f32 v[238:239], v[234:235], v[234:235]
	v_add_f32_e32 v160, 1.0, v160
	v_fmamk_f32 v203, v239, 0xbdd2d3e8, v245
	v_mul_f32_e32 v203, v235, v203
	v_rcp_f32_e32 v161, v161
	v_rcp_f32_e32 v160, v160
	v_exp_f32_e32 v203, v203
	v_pk_mul_f32 v[232:233], v[114:115], v[232:233]
	v_pk_mul_f32 v[152:153], v[152:153], v[160:161]
	v_add_f32_e32 v160, 1.0, v203
	v_rcp_f32_e32 v161, v160
	v_fmamk_f32 v160, v238, 0xbdd2d3e8, v245
	v_mul_f32_e32 v160, v234, v160
	v_exp_f32_e32 v160, v160
	v_pk_mul_f32 v[152:153], v[236:237], v[152:153]
	v_pk_fma_f32 v[232:233], v[230:231], v[126:127], v[232:233]
	v_cndmask_b32_e64 v237, v221, 0, s[94:95]
	v_add_f32_e32 v160, 1.0, v160
	v_rcp_f32_e32 v160, v160
	v_cndmask_b32_e64 v236, v220, 0, s[94:95]
	v_pk_fma_f32 v[232:233], v[236:237], v[130:131], v[232:233]
	v_pk_mul_f32 v[160:161], v[234:235], v[160:161]
	v_pk_add_f32 v[232:233], v[138:139], v[232:233]
	s_nop 0
	v_pk_mul_f32 v[160:161], v[232:233], v[160:161]
	s_nop 0
	v_cvt_pk_bf16_f32 v160, v160, v161
	v_cvt_pk_bf16_f32 v161, v152, v153
	v_mov_b64_e32 v[152:153], s[34:35]
	v_mad_i64_i32 v[152:153], s[12:13], v189, s85, v[152:153]
	v_lshl_add_u64 v[152:153], v[186:187], 1, v[152:153]
	global_store_dwordx2 v[152:153], v[160:161], off

;     __device__ __forceinline__ void operator()(const f32x4 (&acc)[2][2][4][2], const Unit& u, int wr, int wc, int fr, int fq) const {
;     ...
;             for (int j = 0; j < 4; ++j) {
;                 const int cg = cg0 + 4 * n + j;
;                 const float gw0 = cw[cg], gw1 = cw[NUP + cg], gw2 = cw[2 * NUP + cg], gb = cb[cg];
;                 const float vw0 = cw[DFF + cg], vw1 = cw[NUP + DFF + cg], vw2 = cw[2 * NUP + DFF + cg], vb = cb[DFF + cg];
;                 float xg[8], xv[8];
; #pragma unroll
;                 for (int i = 0; i < 8; ++i) { xg[i] = acc[i >> 2][0][i & 3][n][j] * rs[i]; xv[i] = acc[i >> 2][1][i & 3][n][j] * rs[i]; }
;                 const float gp = __builtin_bit_cast(float, __builtin_amdgcn_update_dpp(0, __builtin_bit_cast(int, xg[7]), 0x111, 0xf, 0xf, false));
;                 const float gn = __builtin_bit_cast(float, __builtin_amdgcn_update_dpp(0, __builtin_bit_cast(int, xg[0]), 0x101, 0xf, 0xf, false));
;                 const float vp = __builtin_bit_cast(float, __builtin_amdgcn_update_dpp(0, __builtin_bit_cast(int, xv[7]), 0x111, 0xf, 0xf, false));
;                 const float vn = __builtin_bit_cast(float, __builtin_amdgcn_update_dpp(0, __builtin_bit_cast(int, xv[0]), 0x101, 0xf, 0xf, false));
; #pragma unroll
;                 for (int i = 0; i < 8; ++i) {
;                     float pg = i > 0 ? xg[i - 1] : gp, ng = i < 7 ? xg[i + 1] : gn, pv = i > 0 ? xv[i - 1] : vp, nv = i < 7 ? xv[i + 1] : vn;
;                     if (pz[i]) { pg = 0.f; pv = 0.f; } if (nz[i]) { ng = 0.f; nv = 0.f; }
;                     const float cgv = gw0 * pg + gw1 * xg[i] + gw2 * ng + gb;
;                     const float cvv = vw0 * pv + vw1 * xv[i] + vw2 * nv + vb;
;                     res[i][j] = gelu_tanh(cgv) * cvv;
;                 }
;             }
; #pragma unroll
;             for (int i = 0; i < 8; ++i) { const int s = 8 * fr + i, grow = grow0 + i;
;                 if (s >= 1 && s <= 126 && grow < HALF_TOK) { u32x2 w; w.x = pk2(res[i][0], res[i][1]); w.y = pk2(res[i][2], res[i][3]); *(u32x2*)(G + (size_t)grow * DFF + cg0 + 4 * n) = w; } }
.LBB0_614:
	s_or_b64 exec, exec, s[68:69]
	v_mov_b32_e32 v203, v202
	v_mov_b32_e32 v201, v200
	v_mov_b32_e32 v199, v198
	global_load_dwordx4 v[70:73], v[206:207], off offset:16
	global_load_dwordx4 v[78:81], v[208:209], off offset:2064
	global_load_dwordx4 v[74:77], v[210:211], off offset:16
	global_load_dwordx4 v[82:85], v[204:205], off offset:16
	global_load_dwordx4 v[66:69], v[212:213], off offset:3088
	global_load_dwordx4 v[86:89], v[214:215], off offset:1040
	global_load_dwordx4 v[90:93], v[216:217], off offset:3088
	global_load_dwordx4 v[94:97], v[218:219], off offset:3088
	v_pk_mul_f32 v[98:99], v[46:47], v[202:203]
	v_pk_mul_f32 v[46:47], v[42:43], v[202:203]
	v_pk_mul_f32 v[102:103], v[58:59], v[200:201]
	v_pk_mul_f32 v[100:101], v[50:51], v[200:201]
	v_pk_mul_f32 v[108:109], v[62:63], v[198:199]
	v_pk_mul_f32 v[106:107], v[54:55], v[198:199]
	v_pk_mul_f32 v[48:49], v[48:49], v[202:203]
	v_pk_mul_f32 v[42:43], v[44:45], v[202:203]
	v_pk_mul_f32 v[54:55], v[52:53], v[200:201]
	v_pk_mul_f32 v[64:65], v[64:65], v[198:199]
	v_pk_mul_f32 v[104:105], v[56:57], v[198:199]
	v_mov_b32_dpp v112, v98 row_shr:1 row_mask:0xf bank_mask:0xf bound_ctrl:1
	v_mov_b32_dpp v110, v46 row_shr:1 row_mask:0xf bank_mask:0xf bound_ctrl:1
	v_mov_b32_dpp v113, v99 row_shr:1 row_mask:0xf bank_mask:0xf bound_ctrl:1
	v_mov_b32_dpp v111, v47 row_shr:1 row_mask:0xf bank_mask:0xf bound_ctrl:1
	v_mov_b32_dpp v58, v108 row_shl:1 row_mask:0xf bank_mask:0xf bound_ctrl:1
	v_mov_b32_dpp v50, v106 row_shl:1 row_mask:0xf bank_mask:0xf bound_ctrl:1
	v_mov_b32_dpp v59, v109 row_shl:1 row_mask:0xf bank_mask:0xf bound_ctrl:1
	v_mov_b32_dpp v51, v107 row_shl:1 row_mask:0xf bank_mask:0xf bound_ctrl:1
	v_mov_b32_dpp v114, v48 row_shr:1 row_mask:0xf bank_mask:0xf bound_ctrl:1
	v_mov_b32_dpp v62, v42 row_shr:1 row_mask:0xf bank_mask:0xf bound_ctrl:1
	v_mov_b32_dpp v115, v49 row_shr:1 row_mask:0xf bank_mask:0xf bound_ctrl:1
	v_mov_b32_dpp v63, v43 row_shr:1 row_mask:0xf bank_mask:0xf bound_ctrl:1
	v_pk_mul_f32 v[60:61], v[60:61], v[200:201]
	v_mov_b32_dpp v52, v64 row_shl:1 row_mask:0xf bank_mask:0xf bound_ctrl:1
	v_mov_b32_dpp v44, v104 row_shl:1 row_mask:0xf bank_mask:0xf bound_ctrl:1
	v_mov_b32_dpp v53, v65 row_shl:1 row_mask:0xf bank_mask:0xf bound_ctrl:1
	v_mov_b32_dpp v45, v105 row_shl:1 row_mask:0xf bank_mask:0xf bound_ctrl:1
	s_and_saveexec_b64 s[68:69], s[88:89]
	s_cbranch_execz .LBB0_616
	s_waitcnt vmcnt(7)
	v_pk_mul_f32 v[56:57], v[72:73], v[114:115]
	v_cndmask_b32_e64 v115, v61, 0, s[94:95]
	s_waitcnt vmcnt(6)
	v_pk_fma_f32 v[56:57], v[64:65], v[80:81], v[56:57]
	v_cndmask_b32_e64 v114, v60, 0, s[94:95]
	s_waitcnt vmcnt(5)
	v_pk_fma_f32 v[56:57], v[114:115], v[76:77], v[56:57]
	s_waitcnt vmcnt(3)
	v_pk_mul_f32 v[62:63], v[68:69], v[62:63]
	v_pk_add_f32 v[56:57], v[84:85], v[56:57]
	s_waitcnt vmcnt(2)
	v_pk_fma_f32 v[62:63], v[104:105], v[88:89], v[62:63]
	v_pk_mul_f32 v[114:115], v[56:57], v[56:57]
	v_cndmask_b32_e64 v117, v55, 0, s[94:95]
	v_fmamk_f32 v115, v115, 0xbdd2d3e8, v245
	v_fmamk_f32 v114, v114, 0xbdd2d3e8, v245
	v_mul_f32_e32 v115, v57, v115
	v_mul_f32_e32 v114, v56, v114
	v_cndmask_b32_e64 v116, v54, 0, s[94:95]
	v_pk_mul_f32 v[112:113], v[70:71], v[112:113]
	v_exp_f32_e32 v115, v115
	v_exp_f32_e32 v114, v114
	s_waitcnt vmcnt(1)
	v_pk_fma_f32 v[62:63], v[116:117], v[92:93], v[62:63]
	v_pk_fma_f32 v[112:113], v[108:109], v[78:79], v[112:113]
	v_cndmask_b32_e64 v117, v103, 0, s[94:95]
	v_cndmask_b32_e64 v116, v102, 0, s[94:95]
	v_pk_fma_f32 v[112:113], v[116:117], v[74:75], v[112:113]
	v_add_f32_e32 v115, 1.0, v115
	v_pk_add_f32 v[112:113], v[82:83], v[112:113]
	v_add_f32_e32 v114, 1.0, v114
	v_pk_mul_f32 v[116:117], v[112:113], v[112:113]
	v_rcp_f32_e32 v115, v115
	v_fmamk_f32 v117, v117, 0xbdd2d3e8, v245
	v_rcp_f32_e32 v114, v114
	v_mul_f32_e32 v117, v113, v117
	v_exp_f32_e32 v117, v117
	s_waitcnt vmcnt(0)
	v_pk_add_f32 v[62:63], v[96:97], v[62:63]
	v_pk_mul_f32 v[56:57], v[56:57], v[114:115]
	v_pk_mul_f32 v[110:111], v[66:67], v[110:111]
	v_pk_mul_f32 v[56:57], v[62:63], v[56:57]
	v_add_f32_e32 v62, 1.0, v117
	v_rcp_f32_e32 v63, v62
	v_fmamk_f32 v62, v116, 0xbdd2d3e8, v245
	v_mul_f32_e32 v62, v112, v62
	v_exp_f32_e32 v62, v62
	v_pk_fma_f32 v[110:111], v[106:107], v[86:87], v[110:111]
	v_cndmask_b32_e64 v115, v101, 0, s[94:95]
	v_cndmask_b32_e64 v114, v100, 0, s[94:95]
	v_add_f32_e32 v62, 1.0, v62
	v_rcp_f32_e32 v62, v62
	v_pk_fma_f32 v[110:111], v[114:115], v[90:91], v[110:111]
	v_pk_mul_f32 v[62:63], v[112:113], v[62:63]
	v_pk_add_f32 v[110:111], v[94:95], v[110:111]
	s_nop 0
	v_pk_mul_f32 v[62:63], v[110:111], v[62:63]
	s_nop 0
	v_cvt_pk_bf16_f32 v62, v62, v63
	v_cvt_pk_bf16_f32 v63, v56, v57
	v_mov_b64_e32 v[56:57], s[34:35]
	v_mad_i64_i32 v[56:57], s[70:71], v189, s85, v[56:57]
	v_lshl_add_u64 v[56:57], v[186:187], 1, v[56:57]
	global_store_dwordx2 v[56:57], v[62:63], off offset:8

;     __device__ __forceinline__ void operator()(const f32x4 (&acc)[2][2][4][2], const Unit& u, int wr, int wc, int fr, int fq) const {
;         const int grow0 = 252 * u.pm + 126 * wr - 1 + 8 * fr;
;         const int cg0 = 128 * u.pn + 32 * wc + 8 * fq;
;         float rs[8]; bool pz[8], nz[8];
; #pragma unroll
;         for (int i = 0; i < 8; ++i) { const int t = T0 + grow0 + i; const int tc = t < 0 ? 0 : (t > MTOK - 1 ? MTOK - 1 : t); rs[i] = rstd[tc];
;             pz[i] = ((t & 8191) == 0) && (t != 24576); nz[i] = (((t + 1) & 8191) == 0) && (t + 1 != 24576); }
; #pragma unroll
;         for (int n = 0; n < 2; ++n) {
;             float res[8][4];
; #pragma unroll
;             for (int j = 0; j < 4; ++j) {
;                 const int cg = cg0 + 4 * n + j;
;                 const float gw0 = cw[cg], gw1 = cw[NUP + cg], gw2 = cw[2 * NUP + cg], gb = cb[cg];
;                 const float vw0 = cw[DFF + cg], vw1 = cw[NUP + DFF + cg], vw2 = cw[2 * NUP + DFF + cg], vb = cb[DFF + cg];
;                 float xg[8], xv[8];
; #pragma unroll
;                 for (int i = 0; i < 8; ++i) { xg[i] = acc[i >> 2][0][i & 3][n][j] * rs[i]; xv[i] = acc[i >> 2][1][i & 3][n][j] * rs[i]; }
;                 const float gp = __builtin_bit_cast(float, __builtin_amdgcn_update_dpp(0, __builtin_bit_cast(int, xg[7]), 0x111, 0xf, 0xf, false));
;                 const float gn = __builtin_bit_cast(float, __builtin_amdgcn_update_dpp(0, __builtin_bit_cast(int, xg[0]), 0x101, 0xf, 0xf, false));
;                 const float vp = __builtin_bit_cast(float, __builtin_amdgcn_update_dpp(0, __builtin_bit_cast(int, xv[7]), 0x111, 0xf, 0xf, false));
;                 const float vn = __builtin_bit_cast(float, __builtin_amdgcn_update_dpp(0, __builtin_bit_cast(int, xv[0]), 0x101, 0xf, 0xf, false));
; #pragma unroll
;                 for (int i = 0; i < 8; ++i) {
;                     float pg = i > 0 ? xg[i - 1] : gp, ng = i < 7 ? xg[i + 1] : gn, pv = i > 0 ? xv[i - 1] : vp, nv = i < 7 ? xv[i + 1] : vn;
;                     if (pz[i]) { pg = 0.f; pv = 0.f; } if (nz[i]) { ng = 0.f; nv = 0.f; }
;                     const float cgv = gw0 * pg + gw1 * xg[i] + gw2 * ng + gb;
;                     const float cvv = vw0 * pv + vw1 * xv[i] + vw2 * nv + vb;
;                     res[i][j] = gelu_tanh(cgv) * cvv;
;                 }
;             }
; #pragma unroll
.Lupf_start:
	v_add_u32_e32 v195, 7, v106
	v_med3_i32 v107, v106, 0, s65
	v_add_u32_e32 v203, 1, v106
	v_add_u32_e32 v191, 2, v106
	v_add_u32_e32 v193, 3, v106
	v_add_u32_e32 v201, 4, v106
	v_add_u32_e32 v199, 5, v106
	v_add_u32_e32 v197, 6, v106
	v_med3_i32 v106, v195, 0, s65
	v_lshl_or_b32 v186, s12, 7, v253
	v_lshlrev_b32_e32 v107, 2, v107
	v_med3_i32 v108, v203, 0, s65
	v_lshlrev_b32_e32 v106, 2, v106
	v_ashrrev_i32_e32 v187, 31, v186
	v_lshlrev_b32_e32 v108, 2, v108
	global_load_dword v198, v107, s[42:43]
	global_load_dword v200, v108, s[42:43]
	global_load_dword v202, v106, s[42:43]
	v_lshlrev_b64 v[106:107], 2, v[186:187]
	v_lshl_add_u64 v[206:207], s[52:53], 0, v[106:107]
	s_movk_i32 s10, 0x5000
	v_add_co_u32_e32 v208, vcc, s10, v206
	v_med3_i32 v109, v191, 0, s65
	s_nop 0
	v_addc_co_u32_e32 v209, vcc, 0, v207, vcc
	v_add_co_u32_e32 v210, vcc, s84, v206
	s_mov_b32 s10, 0xd000
	s_nop 0
	v_addc_co_u32_e32 v211, vcc, 0, v207, vcc
	v_add_co_u32_e32 v212, vcc, s66, v206
	v_lshlrev_b32_e32 v188, 2, v109
	s_nop 0
	v_addc_co_u32_e32 v213, vcc, 0, v207, vcc
	v_add_co_u32_e32 v214, vcc, s45, v206
	v_med3_i32 v109, v193, 0, s65
	s_nop 0
	v_addc_co_u32_e32 v215, vcc, 0, v207, vcc
	v_add_co_u32_e32 v216, vcc, s10, v206
	v_lshlrev_b32_e32 v190, 2, v109
	v_med3_i32 v109, v201, 0, s65
	v_lshl_add_u64 v[204:205], s[54:55], 0, v[106:107]
	v_addc_co_u32_e32 v217, vcc, 0, v207, vcc
	v_lshlrev_b32_e32 v192, 2, v109
	v_med3_i32 v109, v199, 0, s65
	v_add_co_u32_e32 v218, vcc, s66, v204
	v_lshlrev_b32_e32 v220, 2, v109
	v_med3_i32 v109, v197, 0, s65
	v_addc_co_u32_e32 v219, vcc, 0, v205, vcc
	v_lshlrev_b32_e32 v221, 2, v109
	global_load_dwordx4 v[106:109], v[206:207], off
	global_load_dwordx4 v[122:125], v[208:209], off offset:2048
	global_load_dwordx4 v[110:113], v[210:211], off
	global_load_dwordx4 v[118:121], v[204:205], off
	global_load_dwordx4 v[114:117], v[212:213], off offset:3072
	global_load_dwordx4 v[126:129], v[214:215], off offset:1024
	global_load_dwordx4 v[130:133], v[216:217], off offset:3072
	global_load_dwordx4 v[138:141], v[218:219], off offset:3072
	global_load_dword v196, v188, s[42:43]
	global_load_dword v194, v190, s[42:43]
	s_nop 0
	global_load_dword v192, v192, s[42:43]
	s_nop 0
	global_load_dword v190, v220, s[42:43]
	global_load_dword v188, v221, s[42:43]
	v_and_b32_e32 v220, 0x1fff, v203
	v_cmp_ne_u32_e32 vcc, s67, v203
	v_cmp_eq_u32_e64 s[10:11], 0, v220
	s_and_b64 s[94:95], vcc, s[10:11]
	v_cmp_gt_i32_e32 vcc, s47, v189
	s_and_b64 s[88:89], s[4:5], vcc
	s_waitcnt vmcnt(0)
	v_pk_mul_f32 v[228:229], v[158:159], v[198:199] op_sel_hi:[1, 0]
	v_pk_mul_f32 v[222:223], v[154:155], v[200:201] op_sel_hi:[1, 0]
	v_pk_mul_f32 v[158:159], v[142:143], v[202:203] op_sel_hi:[1, 0]
	v_pk_mul_f32 v[142:143], v[134:135], v[202:203] op_sel_hi:[1, 0]
	v_pk_mul_f32 v[220:221], v[146:147], v[200:201] op_sel_hi:[1, 0]
	v_pk_mul_f32 v[230:231], v[150:151], v[198:199] op_sel_hi:[1, 0]
	v_pk_mul_f32 v[144:145], v[144:145], v[202:203] op_sel_hi:[1, 0]
	v_pk_mul_f32 v[134:135], v[136:137], v[202:203] op_sel_hi:[1, 0]
	v_pk_mul_f32 v[150:151], v[148:149], v[200:201] op_sel_hi:[1, 0]
	v_pk_mul_f32 v[224:225], v[160:161], v[198:199] op_sel_hi:[1, 0]
	v_pk_mul_f32 v[226:227], v[152:153], v[198:199] op_sel_hi:[1, 0]
	v_mov_b32_dpp v234, v158 row_shr:1 row_mask:0xf bank_mask:0xf bound_ctrl:1
	v_mov_b32_dpp v232, v142 row_shr:1 row_mask:0xf bank_mask:0xf bound_ctrl:1
	v_mov_b32_dpp v235, v159 row_shr:1 row_mask:0xf bank_mask:0xf bound_ctrl:1
	v_mov_b32_dpp v233, v143 row_shr:1 row_mask:0xf bank_mask:0xf bound_ctrl:1
	v_mov_b32_dpp v154, v228 row_shl:1 row_mask:0xf bank_mask:0xf bound_ctrl:1
	v_mov_b32_dpp v146, v230 row_shl:1 row_mask:0xf bank_mask:0xf bound_ctrl:1
	v_mov_b32_dpp v155, v229 row_shl:1 row_mask:0xf bank_mask:0xf bound_ctrl:1
	v_mov_b32_dpp v147, v231 row_shl:1 row_mask:0xf bank_mask:0xf bound_ctrl:1
	v_mov_b32_dpp v238, v144 row_shr:1 row_mask:0xf bank_mask:0xf bound_ctrl:1
	v_mov_b32_dpp v236, v134 row_shr:1 row_mask:0xf bank_mask:0xf bound_ctrl:1
	v_mov_b32_dpp v239, v145 row_shr:1 row_mask:0xf bank_mask:0xf bound_ctrl:1
	v_mov_b32_dpp v237, v135 row_shr:1 row_mask:0xf bank_mask:0xf bound_ctrl:1
	v_pk_mul_f32 v[156:157], v[156:157], v[200:201] op_sel_hi:[1, 0]
	v_mov_b32_dpp v148, v224 row_shl:1 row_mask:0xf bank_mask:0xf bound_ctrl:1
	v_mov_b32_dpp v136, v226 row_shl:1 row_mask:0xf bank_mask:0xf bound_ctrl:1
	v_mov_b32_dpp v149, v225 row_shl:1 row_mask:0xf bank_mask:0xf bound_ctrl:1
	v_mov_b32_dpp v137, v227 row_shl:1 row_mask:0xf bank_mask:0xf bound_ctrl:1
	s_and_saveexec_b64 s[10:11], s[88:89]
	s_cbranch_execz .Lupf_600
	v_pk_fma_f32 v[152:153], v[108:109], v[238:239], v[120:121]
	v_pk_fma_f32 v[152:153], v[224:225], v[124:125], v[152:153]
	v_pk_fma_f32 v[152:153], v[156:157], v[112:113], v[152:153]
	v_pk_fma_f32 v[236:237], v[116:117], v[236:237], v[140:141]
	v_pk_fma_f32 v[236:237], v[226:227], v[128:129], v[236:237]
	v_pk_mul_f32 v[160:161], v[152:153], v[152:153]
	v_fmamk_f32 v161, v161, 0xbdd2d3e8, v245
	v_fmamk_f32 v160, v160, 0xbdd2d3e8, v245
	v_pk_fma_f32 v[234:235], v[106:107], v[234:235], v[118:119]
	v_mul_f32_e32 v161, v153, v161
	v_mul_f32_e32 v160, v152, v160
	v_pk_fma_f32 v[236:237], v[150:151], v[132:133], v[236:237]
	v_pk_fma_f32 v[234:235], v[228:229], v[122:123], v[234:235]
	v_exp_f32_e32 v161, v161
	v_exp_f32_e32 v160, v160
	v_pk_fma_f32 v[234:235], v[222:223], v[110:111], v[234:235]
	v_add_f32_e32 v161, 1.0, v161
	v_pk_mul_f32 v[238:239], v[234:235], v[234:235]
	v_add_f32_e32 v160, 1.0, v160
	v_fmamk_f32 v203, v239, 0xbdd2d3e8, v245
	v_mul_f32_e32 v203, v235, v203
	v_rcp_f32_e32 v161, v161
	v_rcp_f32_e32 v160, v160
	v_exp_f32_e32 v203, v203
	v_pk_fma_f32 v[232:233], v[114:115], v[232:233], v[138:139]
	v_pk_mul_f32 v[152:153], v[152:153], v[160:161]
	v_add_f32_e32 v160, 1.0, v203
	v_rcp_f32_e32 v161, v160
	v_fmamk_f32 v160, v238, 0xbdd2d3e8, v245
	v_mul_f32_e32 v160, v234, v160
	v_exp_f32_e32 v160, v160
	v_pk_mul_f32 v[152:153], v[236:237], v[152:153]
	v_pk_fma_f32 v[232:233], v[230:231], v[126:127], v[232:233]
	v_add_f32_e32 v160, 1.0, v160
	v_rcp_f32_e32 v160, v160
	v_pk_fma_f32 v[232:233], v[220:221], v[130:131], v[232:233]
	v_pk_mul_f32 v[160:161], v[234:235], v[160:161]
	s_nop 0
	v_pk_mul_f32 v[160:161], v[232:233], v[160:161]
	s_nop 0
	v_cvt_pk_bf16_f32 v160, v160, v161
	v_cvt_pk_bf16_f32 v161, v152, v153
	v_mov_b64_e32 v[152:153], s[34:35]
	v_mad_i64_i32 v[152:153], s[12:13], v189, s85, v[152:153]
	v_lshl_add_u64 v[152:153], v[186:187], 1, v[152:153]
	global_store_dwordx2 v[152:153], v[160:161], off
;     __device__ __forceinline__ void operator()(const f32x4 (&acc)[2][2][4][2], const Unit& u, int wr, int wc, int fr, int fq) const {
;     ...
;                 for (int i = 0; i < 8; ++i) {
;                     float pg = i > 0 ? xg[i - 1] : gp, ng = i < 7 ? xg[i + 1] : gn, pv = i > 0 ? xv[i - 1] : vp, nv = i < 7 ? xv[i + 1] : vn;
;                     if (pz[i]) { pg = 0.f; pv = 0.f; } if (nz[i]) { ng = 0.f; nv = 0.f; }
;                     const float cgv = gw0 * pg + gw1 * xg[i] + gw2 * ng + gb;
;                     const float cvv = vw0 * pv + vw1 * xv[i] + vw2 * nv + vb;
;                     res[i][j] = gelu_tanh(cgv) * cvv;
;                 }
;             }
; #pragma unroll
;             for (int i = 0; i < 8; ++i) { const int s = 8 * fr + i, grow = grow0 + i;
;                 if (s >= 1 && s <= 126 && grow < HALF_TOK) { u32x2 w; w.x = pk2(res[i][0], res[i][1]); w.y = pk2(res[i][2], res[i][3]); *(u32x2*)(G + (size_t)grow * DFF + cg0 + 4 * n) = w; } }
.Lupf_600:
	s_or_b64 exec, exec, s[10:11]
	v_and_b32_e32 v152, 0x1fff, v191
	s_movk_i32 s10, 0x3fff
	v_cmp_eq_u32_e32 vcc, 0, v152
	v_pk_mul_f32 v[160:161], v[102:103], v[196:197] op_sel_hi:[1, 0]
	v_pk_mul_f32 v[152:153], v[98:99], v[196:197] op_sel_hi:[1, 0]
	v_pk_mul_f32 v[102:103], v[104:105], v[196:197] op_sel_hi:[1, 0]
	v_pk_mul_f32 v[98:99], v[100:101], v[196:197] op_sel_hi:[1, 0]
	v_add_u32_e32 v191, 1, v189
	v_cmp_gt_i32_e64 s[14:15], s10, v189
	s_and_saveexec_b64 s[10:11], s[14:15]
	s_cbranch_execz .Lupf_602
	v_mov_b32_e32 v101, v229
	v_mov_b32_e32 v100, v228
	v_pk_fma_f32 v[232:233], v[222:223], v[122:123], v[118:119]
	v_cndmask_b32_e64 v229, v161, 0, vcc
	v_cndmask_b32_e64 v228, v160, 0, vcc
	v_pk_fma_f32 v[100:101], v[100:101], v[106:107], v[232:233]
	v_mov_b32_e32 v105, v231
	v_pk_fma_f32 v[100:101], v[228:229], v[110:111], v[100:101]
	v_mov_b32_e32 v104, v230
	v_cndmask_b32_e64 v231, v153, 0, vcc
	v_pk_mul_f32 v[228:229], v[100:101], v[100:101]
	v_cndmask_b32_e64 v230, v152, 0, vcc
	v_fmamk_f32 v203, v228, 0xbdd2d3e8, v245
	v_mul_f32_e32 v203, v100, v203
	v_fmamk_f32 v228, v229, 0xbdd2d3e8, v245
	v_exp_f32_e32 v203, v203
	v_mul_f32_e32 v228, v101, v228
	v_exp_f32_e32 v233, v228
	v_pk_fma_f32 v[228:229], v[220:221], v[126:127], v[138:139]
	v_add_f32_e32 v203, 1.0, v203
	v_rcp_f32_e32 v232, v203
	v_add_f32_e32 v203, 1.0, v233
	v_rcp_f32_e32 v233, v203
	v_pk_fma_f32 v[104:105], v[104:105], v[114:115], v[228:229]
	v_cndmask_b32_e64 v229, v99, 0, vcc
	v_pk_fma_f32 v[104:105], v[230:231], v[130:131], v[104:105]
	v_pk_mul_f32 v[100:101], v[100:101], v[232:233]
	v_pk_fma_f32 v[230:231], v[156:157], v[124:125], v[120:121]
	v_pk_mul_f32 v[100:101], v[104:105], v[100:101]
	v_mov_b32_e32 v105, v225
	v_mov_b32_e32 v104, v224
	v_mov_b32_e32 v225, v227
	v_mov_b32_e32 v224, v226
	v_cndmask_b32_e64 v227, v103, 0, vcc
	v_cndmask_b32_e64 v226, v102, 0, vcc
	v_pk_fma_f32 v[104:105], v[104:105], v[108:109], v[230:231]
	v_cndmask_b32_e64 v228, v98, 0, vcc
	v_pk_fma_f32 v[104:105], v[226:227], v[112:113], v[104:105]
	v_cvt_pk_bf16_f32 v100, v100, v101
	s_nop 0
	v_pk_mul_f32 v[226:227], v[104:105], v[104:105]
	s_nop 0
	v_fmamk_f32 v203, v226, 0xbdd2d3e8, v245
	v_mul_f32_e32 v203, v104, v203
	v_fmamk_f32 v226, v227, 0xbdd2d3e8, v245
	v_exp_f32_e32 v203, v203
	v_mul_f32_e32 v226, v105, v226
	v_exp_f32_e32 v231, v226
	v_pk_fma_f32 v[226:227], v[150:151], v[128:129], v[140:141]
	v_add_f32_e32 v203, 1.0, v203
	v_rcp_f32_e32 v230, v203
	v_add_f32_e32 v203, 1.0, v231
	v_rcp_f32_e32 v231, v203
	v_pk_fma_f32 v[224:225], v[224:225], v[116:117], v[226:227]
	v_pk_mul_f32 v[104:105], v[104:105], v[230:231]
	v_pk_fma_f32 v[224:225], v[228:229], v[132:133], v[224:225]
	s_nop 0
	s_nop 0
	v_pk_mul_f32 v[104:105], v[224:225], v[104:105]
	s_nop 0
	v_cvt_pk_bf16_f32 v101, v104, v105
	v_mov_b64_e32 v[104:105], s[34:35]
	v_mad_i64_i32 v[104:105], s[12:13], v191, s85, v[104:105]
	v_lshl_add_u64 v[104:105], v[186:187], 1, v[104:105]
	global_store_dwordx2 v[104:105], v[100:101], off
.Lupf_602:
	s_or_b64 exec, exec, s[10:11]
	v_and_b32_e32 v100, 0x1fff, v193
	v_cmp_eq_u32_e64 s[10:11], 0, v100
	v_cmp_ne_u32_e64 s[12:13], s67, v193
	s_and_b64 s[96:97], s[12:13], s[10:11]
	s_movk_i32 s10, 0x3ffe
	v_pk_mul_f32 v[104:105], v[94:95], v[194:195] op_sel_hi:[1, 0]
	v_pk_mul_f32 v[100:101], v[90:91], v[194:195] op_sel_hi:[1, 0]
	v_pk_mul_f32 v[94:95], v[96:97], v[194:195] op_sel_hi:[1, 0]
	v_pk_mul_f32 v[90:91], v[92:93], v[194:195] op_sel_hi:[1, 0]
	v_add_u32_e32 v193, 2, v189
	v_cmp_gt_i32_e64 s[16:17], s10, v189
	s_and_saveexec_b64 s[10:11], s[16:17]
	s_cbranch_execz .Lupf_604
	v_cndmask_b32_e64 v93, v223, 0, vcc
	v_cndmask_b32_e64 v92, v222, 0, vcc
	v_pk_fma_f32 v[224:225], v[160:161], v[122:123], v[118:119]
	v_cndmask_b32_e64 v97, v221, 0, vcc
	v_cndmask_b32_e64 v96, v220, 0, vcc
	v_pk_fma_f32 v[92:93], v[92:93], v[106:107], v[224:225]
	v_pk_fma_f32 v[92:93], v[104:105], v[110:111], v[92:93]
	v_cndmask_b32_e64 v151, v151, 0, vcc
	v_pk_mul_f32 v[220:221], v[92:93], v[92:93]
	v_cndmask_b32_e64 v150, v150, 0, vcc
	v_fmamk_f32 v203, v220, 0xbdd2d3e8, v245
	v_mul_f32_e32 v203, v92, v203
	v_fmamk_f32 v220, v221, 0xbdd2d3e8, v245
	v_exp_f32_e32 v203, v203
	v_mul_f32_e32 v220, v93, v220
	v_exp_f32_e32 v225, v220
	v_pk_fma_f32 v[220:221], v[152:153], v[126:127], v[138:139]
	v_add_f32_e32 v203, 1.0, v203
	v_rcp_f32_e32 v224, v203
	v_add_f32_e32 v203, 1.0, v225
	v_rcp_f32_e32 v225, v203
	v_pk_fma_f32 v[96:97], v[96:97], v[114:115], v[220:221]
	v_pk_fma_f32 v[96:97], v[100:101], v[130:131], v[96:97]
	v_pk_mul_f32 v[92:93], v[92:93], v[224:225]
	v_pk_fma_f32 v[222:223], v[102:103], v[124:125], v[120:121]
	v_pk_mul_f32 v[92:93], v[96:97], v[92:93]
	v_cndmask_b32_e64 v97, v157, 0, vcc
	v_cndmask_b32_e64 v96, v156, 0, vcc
	v_pk_fma_f32 v[96:97], v[96:97], v[108:109], v[222:223]
	v_pk_fma_f32 v[96:97], v[94:95], v[112:113], v[96:97]
	v_cvt_pk_bf16_f32 v92, v92, v93
	s_nop 0
	v_pk_mul_f32 v[156:157], v[96:97], v[96:97]
	s_nop 0
	v_fmamk_f32 v156, v156, 0xbdd2d3e8, v245
	v_mul_f32_e32 v156, v96, v156
	v_exp_f32_e32 v203, v156
	v_fmamk_f32 v156, v157, 0xbdd2d3e8, v245
	v_mul_f32_e32 v156, v97, v156
	v_exp_f32_e32 v223, v156
	v_add_f32_e32 v203, 1.0, v203
	v_rcp_f32_e32 v222, v203
	v_pk_fma_f32 v[156:157], v[98:99], v[128:129], v[140:141]
	v_add_f32_e32 v203, 1.0, v223
	v_rcp_f32_e32 v223, v203
	v_pk_fma_f32 v[150:151], v[150:151], v[116:117], v[156:157]
	v_pk_mul_f32 v[96:97], v[96:97], v[222:223]
	v_pk_fma_f32 v[150:151], v[90:91], v[132:133], v[150:151]
	s_nop 0
	s_nop 0
	v_pk_mul_f32 v[96:97], v[150:151], v[96:97]
	s_nop 0
	v_cvt_pk_bf16_f32 v93, v96, v97
	v_mov_b64_e32 v[96:97], s[34:35]
	v_mad_i64_i32 v[96:97], s[12:13], v193, s85, v[96:97]
	v_lshl_add_u64 v[96:97], v[186:187], 1, v[96:97]
	global_store_dwordx2 v[96:97], v[92:93], off
;     __device__ __forceinline__ void operator()(const f32x4 (&acc)[2][2][4][2], const Unit& u, int wr, int wc, int fr, int fq) const {
;     ...
;                 for (int i = 0; i < 8; ++i) {
;                     float pg = i > 0 ? xg[i - 1] : gp, ng = i < 7 ? xg[i + 1] : gn, pv = i > 0 ? xv[i - 1] : vp, nv = i < 7 ? xv[i + 1] : vn;
;                     if (pz[i]) { pg = 0.f; pv = 0.f; } if (nz[i]) { ng = 0.f; nv = 0.f; }
;                     const float cgv = gw0 * pg + gw1 * xg[i] + gw2 * ng + gb;
;                     const float cvv = vw0 * pv + vw1 * xv[i] + vw2 * nv + vb;
;                     res[i][j] = gelu_tanh(cgv) * cvv;
;                 }
;             }
; #pragma unroll
;             for (int i = 0; i < 8; ++i) { const int s = 8 * fr + i, grow = grow0 + i;
;                 if (s >= 1 && s <= 126 && grow < HALF_TOK) { u32x2 w; w.x = pk2(res[i][0], res[i][1]); w.y = pk2(res[i][2], res[i][3]); *(u32x2*)(G + (size_t)grow * DFF + cg0 + 4 * n) = w; } }
.Lupf_604:
	s_or_b64 exec, exec, s[10:11]
	v_and_b32_e32 v92, 0x1fff, v201
	s_movk_i32 s12, 0x3ffd
	v_cmp_eq_u32_e64 s[10:11], 0, v92
	v_pk_mul_f32 v[96:97], v[86:87], v[192:193] op_sel_hi:[1, 0]
	v_pk_mul_f32 v[92:93], v[82:83], v[192:193] op_sel_hi:[1, 0]
	v_pk_mul_f32 v[86:87], v[88:89], v[192:193] op_sel_hi:[1, 0]
	v_pk_mul_f32 v[82:83], v[84:85], v[192:193] op_sel_hi:[1, 0]
	v_add_u32_e32 v150, 3, v189
	v_cmp_gt_i32_e64 s[18:19], s12, v189
	s_and_saveexec_b64 s[12:13], s[18:19]
	s_cbranch_execz .Lupf_606
	v_mov_b32_e32 v85, v161
	v_mov_b32_e32 v84, v160
	v_pk_fma_f32 v[160:161], v[104:105], v[122:123], v[118:119]
	v_mov_b32_e32 v89, v153
	v_mov_b32_e32 v88, v152
	v_pk_fma_f32 v[84:85], v[84:85], v[106:107], v[160:161]
	v_pk_fma_f32 v[84:85], v[96:97], v[110:111], v[84:85]
	v_pk_mul_f32 v[152:153], v[84:85], v[84:85]
	v_fmamk_f32 v151, v152, 0xbdd2d3e8, v245
	v_mul_f32_e32 v151, v84, v151
	v_fmamk_f32 v152, v153, 0xbdd2d3e8, v245
	v_exp_f32_e32 v151, v151
	v_mul_f32_e32 v152, v85, v152
	v_exp_f32_e32 v161, v152
	v_pk_fma_f32 v[152:153], v[100:101], v[126:127], v[138:139]
	v_add_f32_e32 v151, 1.0, v151
	v_rcp_f32_e32 v160, v151
	v_add_f32_e32 v151, 1.0, v161
	v_rcp_f32_e32 v161, v151
	v_pk_fma_f32 v[88:89], v[88:89], v[114:115], v[152:153]
	v_pk_fma_f32 v[88:89], v[92:93], v[130:131], v[88:89]
	v_pk_mul_f32 v[84:85], v[84:85], v[160:161]
	v_pk_fma_f32 v[156:157], v[94:95], v[124:125], v[120:121]
	v_pk_mul_f32 v[84:85], v[88:89], v[84:85]
	v_pk_fma_f32 v[88:89], v[102:103], v[108:109], v[156:157]
	v_pk_fma_f32 v[88:89], v[86:87], v[112:113], v[88:89]
	v_cvt_pk_bf16_f32 v84, v84, v85
	s_nop 0
	v_pk_mul_f32 v[102:103], v[88:89], v[88:89]
	s_nop 0
	v_fmamk_f32 v102, v102, 0xbdd2d3e8, v245
	v_mul_f32_e32 v102, v88, v102
	v_exp_f32_e32 v151, v102
	v_fmamk_f32 v102, v103, 0xbdd2d3e8, v245
	v_mul_f32_e32 v102, v89, v102
	v_exp_f32_e32 v157, v102
	v_add_f32_e32 v151, 1.0, v151
	v_rcp_f32_e32 v156, v151
	v_pk_fma_f32 v[102:103], v[90:91], v[128:129], v[140:141]
	v_add_f32_e32 v151, 1.0, v157
	v_rcp_f32_e32 v157, v151
	v_pk_fma_f32 v[98:99], v[98:99], v[116:117], v[102:103]
	v_pk_mul_f32 v[88:89], v[88:89], v[156:157]
	v_pk_fma_f32 v[98:99], v[82:83], v[132:133], v[98:99]
	s_nop 0
	s_nop 0
	v_pk_mul_f32 v[88:89], v[98:99], v[88:89]
	s_nop 0
	v_cvt_pk_bf16_f32 v85, v88, v89
	v_mov_b64_e32 v[88:89], s[34:35]
	v_mad_i64_i32 v[88:89], s[20:21], v150, s85, v[88:89]
	v_lshl_add_u64 v[88:89], v[186:187], 1, v[88:89]
	global_store_dwordx2 v[88:89], v[84:85], off
.Lupf_606:
	s_or_b64 exec, exec, s[12:13]
	v_and_b32_e32 v84, 0x1fff, v199
	v_cmp_eq_u32_e64 s[12:13], 0, v84
	v_cmp_ne_u32_e64 s[20:21], s67, v199
	s_and_b64 s[82:83], s[20:21], s[12:13]
	s_movk_i32 s12, 0x3ffc
	v_pk_mul_f32 v[88:89], v[78:79], v[190:191] op_sel_hi:[1, 0]
	v_pk_mul_f32 v[84:85], v[74:75], v[190:191] op_sel_hi:[1, 0]
	v_pk_mul_f32 v[78:79], v[80:81], v[190:191] op_sel_hi:[1, 0]
	v_pk_mul_f32 v[74:75], v[76:77], v[190:191] op_sel_hi:[1, 0]
	v_add_u32_e32 v151, 4, v189
	v_cmp_gt_i32_e64 s[20:21], s12, v189
	s_and_saveexec_b64 s[12:13], s[20:21]
	s_cbranch_execz .Lupf_608
	v_pk_fma_f32 v[102:103], v[96:97], v[122:123], v[118:119]
	v_pk_fma_f32 v[76:77], v[104:105], v[106:107], v[102:103]
	v_pk_fma_f32 v[76:77], v[88:89], v[110:111], v[76:77]
	v_pk_mul_f32 v[98:99], v[76:77], v[76:77]
	v_fmamk_f32 v98, v98, 0xbdd2d3e8, v245
	v_mul_f32_e32 v98, v76, v98
	v_exp_f32_e32 v102, v98
	v_fmamk_f32 v98, v99, 0xbdd2d3e8, v245
	v_mul_f32_e32 v98, v77, v98
	v_exp_f32_e32 v103, v98
	v_add_f32_e32 v102, 1.0, v102
	v_rcp_f32_e32 v102, v102
	v_pk_fma_f32 v[98:99], v[92:93], v[126:127], v[138:139]
	v_add_f32_e32 v103, 1.0, v103
	v_rcp_f32_e32 v103, v103
	v_pk_fma_f32 v[80:81], v[100:101], v[114:115], v[98:99]
	v_pk_fma_f32 v[80:81], v[84:85], v[130:131], v[80:81]
	v_pk_mul_f32 v[76:77], v[76:77], v[102:103]
	v_pk_fma_f32 v[100:101], v[86:87], v[124:125], v[120:121]
	v_pk_mul_f32 v[76:77], v[80:81], v[76:77]
	v_pk_fma_f32 v[80:81], v[94:95], v[108:109], v[100:101]
	v_pk_fma_f32 v[80:81], v[78:79], v[112:113], v[80:81]
	v_pk_mul_f32 v[94:95], v[80:81], v[80:81]
	v_cvt_pk_bf16_f32 v76, v76, v77
	v_fmamk_f32 v94, v94, 0xbdd2d3e8, v245
	v_mul_f32_e32 v94, v80, v94
	v_exp_f32_e32 v100, v94
	v_fmamk_f32 v94, v95, 0xbdd2d3e8, v245
	v_mul_f32_e32 v94, v81, v94
	v_exp_f32_e32 v101, v94
	v_add_f32_e32 v100, 1.0, v100
	v_rcp_f32_e32 v100, v100
	v_pk_fma_f32 v[94:95], v[82:83], v[128:129], v[140:141]
	v_add_f32_e32 v101, 1.0, v101
	v_rcp_f32_e32 v101, v101
	v_pk_fma_f32 v[90:91], v[90:91], v[116:117], v[94:95]
	v_pk_mul_f32 v[80:81], v[80:81], v[100:101]
	v_pk_fma_f32 v[90:91], v[74:75], v[132:133], v[90:91]
	s_nop 0
	s_nop 0
	v_pk_mul_f32 v[80:81], v[90:91], v[80:81]
	s_nop 0
	v_cvt_pk_bf16_f32 v77, v80, v81
	v_mov_b64_e32 v[80:81], s[34:35]
	v_mad_i64_i32 v[80:81], s[22:23], v151, s85, v[80:81]
	v_lshl_add_u64 v[80:81], v[186:187], 1, v[80:81]
	global_store_dwordx2 v[80:81], v[76:77], off
;     __device__ __forceinline__ void operator()(const f32x4 (&acc)[2][2][4][2], const Unit& u, int wr, int wc, int fr, int fq) const {
;     ...
;                 for (int i = 0; i < 8; ++i) {
;                     float pg = i > 0 ? xg[i - 1] : gp, ng = i < 7 ? xg[i + 1] : gn, pv = i > 0 ? xv[i - 1] : vp, nv = i < 7 ? xv[i + 1] : vn;
;                     if (pz[i]) { pg = 0.f; pv = 0.f; } if (nz[i]) { ng = 0.f; nv = 0.f; }
;                     const float cgv = gw0 * pg + gw1 * xg[i] + gw2 * ng + gb;
;                     const float cvv = vw0 * pv + vw1 * xv[i] + vw2 * nv + vb;
;                     res[i][j] = gelu_tanh(cgv) * cvv;
;                 }
;             }
; #pragma unroll
;             for (int i = 0; i < 8; ++i) { const int s = 8 * fr + i, grow = grow0 + i;
;                 if (s >= 1 && s <= 126 && grow < HALF_TOK) { u32x2 w; w.x = pk2(res[i][0], res[i][1]); w.y = pk2(res[i][2], res[i][3]); *(u32x2*)(G + (size_t)grow * DFF + cg0 + 4 * n) = w; } }
.Lupf_608:
	s_or_b64 exec, exec, s[12:13]
	v_and_b32_e32 v76, 0x1fff, v197
	s_movk_i32 s22, 0x3ffb
	v_cmp_eq_u32_e64 s[12:13], 0, v76
	v_pk_mul_f32 v[80:81], v[70:71], v[188:189] op_sel_hi:[1, 0]
	v_pk_mul_f32 v[76:77], v[66:67], v[188:189] op_sel_hi:[1, 0]
	v_pk_mul_f32 v[70:71], v[72:73], v[188:189] op_sel_hi:[1, 0]
	v_pk_mul_f32 v[66:67], v[68:69], v[188:189] op_sel_hi:[1, 0]
	v_add_u32_e32 v152, 5, v189
	v_cmp_gt_i32_e64 s[22:23], s22, v189
	s_and_saveexec_b64 s[24:25], s[22:23]
	s_cbranch_execz .Lupf_610
	v_pk_fma_f32 v[94:95], v[88:89], v[122:123], v[118:119]
	v_pk_fma_f32 v[68:69], v[96:97], v[106:107], v[94:95]
	v_pk_fma_f32 v[68:69], v[80:81], v[110:111], v[68:69]
	v_pk_fma_f32 v[94:95], v[84:85], v[126:127], v[138:139]
	v_pk_mul_f32 v[90:91], v[68:69], v[68:69]
	v_fmamk_f32 v90, v90, 0xbdd2d3e8, v245
	v_fmamk_f32 v91, v91, 0xbdd2d3e8, v245
	v_mul_f32_e32 v90, v68, v90
	v_mul_f32_e32 v91, v69, v91
	v_exp_f32_e32 v90, v90
	v_exp_f32_e32 v91, v91
	v_pk_fma_f32 v[72:73], v[92:93], v[114:115], v[94:95]
	v_add_f32_e32 v90, 1.0, v90
	v_add_f32_e32 v91, 1.0, v91
	v_rcp_f32_e32 v90, v90
	v_rcp_f32_e32 v91, v91
	v_pk_fma_f32 v[72:73], v[76:77], v[130:131], v[72:73]
	v_pk_fma_f32 v[92:93], v[78:79], v[124:125], v[120:121]
	v_pk_mul_f32 v[68:69], v[68:69], v[90:91]
	v_pk_mul_f32 v[68:69], v[72:73], v[68:69]
	v_pk_fma_f32 v[72:73], v[86:87], v[108:109], v[92:93]
	v_pk_fma_f32 v[72:73], v[70:71], v[112:113], v[72:73]
	v_pk_fma_f32 v[92:93], v[74:75], v[128:129], v[140:141]
	v_pk_mul_f32 v[86:87], v[72:73], v[72:73]
	v_fmamk_f32 v86, v86, 0xbdd2d3e8, v245
	v_fmamk_f32 v87, v87, 0xbdd2d3e8, v245
	v_mul_f32_e32 v86, v72, v86
	v_mul_f32_e32 v87, v73, v87
	v_exp_f32_e32 v86, v86
	v_exp_f32_e32 v87, v87
	v_pk_fma_f32 v[82:83], v[82:83], v[116:117], v[92:93]
	v_cvt_pk_bf16_f32 v68, v68, v69
	v_add_f32_e32 v86, 1.0, v86
	v_add_f32_e32 v87, 1.0, v87
	v_rcp_f32_e32 v86, v86
	v_rcp_f32_e32 v87, v87
	v_pk_fma_f32 v[82:83], v[66:67], v[132:133], v[82:83]
	v_pk_mul_f32 v[72:73], v[72:73], v[86:87]
	s_nop 0
	v_pk_mul_f32 v[72:73], v[82:83], v[72:73]
	s_nop 0
	v_cvt_pk_bf16_f32 v69, v72, v73
	v_mov_b64_e32 v[72:73], s[34:35]
	v_mad_i64_i32 v[72:73], s[28:29], v152, s85, v[72:73]
	v_lshl_add_u64 v[72:73], v[186:187], 1, v[72:73]
	global_store_dwordx2 v[72:73], v[68:69], off
.Lupf_610:
	s_or_b64 exec, exec, s[24:25]
	v_and_b32_e32 v68, 0x1fff, v195
	v_cmp_eq_u32_e64 s[24:25], 0, v68
	v_cmp_ne_u32_e64 s[28:29], s67, v195
	s_and_b64 s[86:87], s[28:29], s[24:25]
	s_movk_i32 s24, 0x3ffa
	v_add_u32_e32 v153, 6, v189
	v_cmp_gt_i32_e64 s[24:25], s24, v189
	s_and_saveexec_b64 s[28:29], s[24:25]
	s_cbranch_execz .Lupf_612
	v_pk_fma_f32 v[82:83], v[80:81], v[122:123], v[118:119]
	v_pk_fma_f32 v[68:69], v[88:89], v[106:107], v[82:83]
	v_pk_fma_f32 v[68:69], v[158:159], v[110:111], v[68:69]
	v_pk_fma_f32 v[86:87], v[76:77], v[126:127], v[138:139]
	v_pk_mul_f32 v[72:73], v[68:69], v[68:69]
	v_fmamk_f32 v72, v72, 0xbdd2d3e8, v245
	v_fmamk_f32 v73, v73, 0xbdd2d3e8, v245
	v_mul_f32_e32 v72, v68, v72
	v_mul_f32_e32 v73, v69, v73
	v_exp_f32_e32 v72, v72
	v_exp_f32_e32 v73, v73
	v_pk_fma_f32 v[82:83], v[84:85], v[114:115], v[86:87]
	v_add_f32_e32 v72, 1.0, v72
	v_add_f32_e32 v73, 1.0, v73
	v_rcp_f32_e32 v72, v72
	v_rcp_f32_e32 v73, v73
	v_pk_fma_f32 v[82:83], v[142:143], v[130:131], v[82:83]
	v_pk_fma_f32 v[84:85], v[70:71], v[124:125], v[120:121]
	v_pk_mul_f32 v[68:69], v[68:69], v[72:73]
	v_pk_fma_f32 v[72:73], v[78:79], v[108:109], v[84:85]
	v_pk_fma_f32 v[72:73], v[144:145], v[112:113], v[72:73]
	v_pk_fma_f32 v[84:85], v[66:67], v[128:129], v[140:141]
	v_pk_mul_f32 v[78:79], v[72:73], v[72:73]
	v_pk_mul_f32 v[68:69], v[82:83], v[68:69]
	v_fmamk_f32 v78, v78, 0xbdd2d3e8, v245
	v_fmamk_f32 v79, v79, 0xbdd2d3e8, v245
	v_mul_f32_e32 v78, v72, v78
	v_mul_f32_e32 v79, v73, v79
	v_exp_f32_e32 v78, v78
	v_exp_f32_e32 v79, v79
	v_add_f32_e32 v78, 1.0, v78
	v_add_f32_e32 v79, 1.0, v79
	v_rcp_f32_e32 v78, v78
	v_rcp_f32_e32 v79, v79
	v_pk_fma_f32 v[74:75], v[74:75], v[116:117], v[84:85]
	v_cvt_pk_bf16_f32 v68, v68, v69
	v_pk_fma_f32 v[74:75], v[134:135], v[132:133], v[74:75]
	v_pk_mul_f32 v[72:73], v[72:73], v[78:79]
	s_nop 0
	v_pk_mul_f32 v[72:73], v[74:75], v[72:73]
	s_nop 0
	v_cvt_pk_bf16_f32 v69, v72, v73
	v_mov_b64_e32 v[72:73], s[34:35]
	v_mad_i64_i32 v[72:73], s[68:69], v153, s85, v[72:73]
	v_lshl_add_u64 v[72:73], v[186:187], 1, v[72:73]
	global_store_dwordx2 v[72:73], v[68:69], off
.Lupf_612:
	s_or_b64 exec, exec, s[28:29]
	s_movk_i32 s28, 0x3ff9
	v_cmp_gt_i32_e64 s[28:29], s28, v189
	v_add_u32_e32 v156, 7, v189
	s_and_b64 s[28:29], s[6:7], s[28:29]
	s_and_saveexec_b64 s[68:69], s[28:29]
	s_cbranch_execz .Lupf_614
	v_pk_fma_f32 v[72:73], v[158:159], v[122:123], v[118:119]
	v_pk_fma_f32 v[68:69], v[106:107], v[80:81], v[72:73]
	v_mov_b32_e32 v72, v76
	v_pk_fma_f32 v[68:69], v[110:111], v[154:155], v[68:69]
	v_mov_b32_e32 v73, v77
	v_pk_mul_f32 v[74:75], v[68:69], v[68:69]
	v_fmamk_f32 v74, v74, 0xbdd2d3e8, v245
	v_mul_f32_e32 v74, v68, v74
	v_exp_f32_e32 v76, v74
	v_fmamk_f32 v74, v75, 0xbdd2d3e8, v245
	v_mul_f32_e32 v74, v69, v74
	v_exp_f32_e32 v77, v74
	v_add_f32_e32 v76, 1.0, v76
	v_rcp_f32_e32 v76, v76
	v_pk_fma_f32 v[74:75], v[142:143], v[126:127], v[138:139]
	v_add_f32_e32 v77, 1.0, v77
	v_rcp_f32_e32 v77, v77
	v_pk_fma_f32 v[72:73], v[72:73], v[114:115], v[74:75]
	v_pk_fma_f32 v[72:73], v[130:131], v[146:147], v[72:73]
	v_pk_mul_f32 v[68:69], v[68:69], v[76:77]
	s_nop 0
	v_pk_mul_f32 v[68:69], v[72:73], v[68:69]
	v_pk_fma_f32 v[72:73], v[144:145], v[124:125], v[120:121]
	v_cvt_pk_bf16_f32 v68, v68, v69
	v_pk_fma_f32 v[70:71], v[70:71], v[108:109], v[72:73]
	s_nop 0
	v_pk_fma_f32 v[70:71], v[112:113], v[148:149], v[70:71]
	s_nop 0
	s_nop 0
	v_pk_mul_f32 v[72:73], v[70:71], v[70:71]
	s_nop 0
	v_fmamk_f32 v72, v72, 0xbdd2d3e8, v245
	v_mul_f32_e32 v72, v70, v72
	v_exp_f32_e32 v74, v72
	v_fmamk_f32 v72, v73, 0xbdd2d3e8, v245
	v_mul_f32_e32 v72, v71, v72
	v_exp_f32_e32 v75, v72
	v_add_f32_e32 v74, 1.0, v74
	v_rcp_f32_e32 v74, v74
	v_pk_fma_f32 v[72:73], v[134:135], v[128:129], v[140:141]
	v_add_f32_e32 v75, 1.0, v75
	v_rcp_f32_e32 v75, v75
	v_pk_fma_f32 v[66:67], v[66:67], v[116:117], v[72:73]
	v_pk_mul_f32 v[70:71], v[70:71], v[74:75]
	v_pk_fma_f32 v[66:67], v[132:133], v[136:137], v[66:67]
	s_nop 0
	s_nop 0
	v_pk_mul_f32 v[66:67], v[66:67], v[70:71]
	s_nop 0
	v_cvt_pk_bf16_f32 v69, v66, v67
	v_mov_b64_e32 v[66:67], s[34:35]
	v_mad_i64_i32 v[66:67], s[70:71], v156, s85, v[66:67]
	v_lshl_add_u64 v[66:67], v[186:187], 1, v[66:67]
	global_store_dwordx2 v[66:67], v[68:69], off
;     __device__ __forceinline__ void operator()(const f32x4 (&acc)[2][2][4][2], const Unit& u, int wr, int wc, int fr, int fq) const {
;     ...
;             for (int j = 0; j < 4; ++j) {
;                 const int cg = cg0 + 4 * n + j;
;                 const float gw0 = cw[cg], gw1 = cw[NUP + cg], gw2 = cw[2 * NUP + cg], gb = cb[cg];
;                 const float vw0 = cw[DFF + cg], vw1 = cw[NUP + DFF + cg], vw2 = cw[2 * NUP + DFF + cg], vb = cb[DFF + cg];
;                 float xg[8], xv[8];
; #pragma unroll
;                 for (int i = 0; i < 8; ++i) { xg[i] = acc[i >> 2][0][i & 3][n][j] * rs[i]; xv[i] = acc[i >> 2][1][i & 3][n][j] * rs[i]; }
;                 const float gp = __builtin_bit_cast(float, __builtin_amdgcn_update_dpp(0, __builtin_bit_cast(int, xg[7]), 0x111, 0xf, 0xf, false));
;                 const float gn = __builtin_bit_cast(float, __builtin_amdgcn_update_dpp(0, __builtin_bit_cast(int, xg[0]), 0x101, 0xf, 0xf, false));
;                 const float vp = __builtin_bit_cast(float, __builtin_amdgcn_update_dpp(0, __builtin_bit_cast(int, xv[7]), 0x111, 0xf, 0xf, false));
;                 const float vn = __builtin_bit_cast(float, __builtin_amdgcn_update_dpp(0, __builtin_bit_cast(int, xv[0]), 0x101, 0xf, 0xf, false));
; #pragma unroll
;                 for (int i = 0; i < 8; ++i) {
;                     float pg = i > 0 ? xg[i - 1] : gp, ng = i < 7 ? xg[i + 1] : gn, pv = i > 0 ? xv[i - 1] : vp, nv = i < 7 ? xv[i + 1] : vn;
;                     if (pz[i]) { pg = 0.f; pv = 0.f; } if (nz[i]) { ng = 0.f; nv = 0.f; }
;                     const float cgv = gw0 * pg + gw1 * xg[i] + gw2 * ng + gb;
;                     const float cvv = vw0 * pv + vw1 * xv[i] + vw2 * nv + vb;
;                     res[i][j] = gelu_tanh(cgv) * cvv;
;                 }
;             }
; #pragma unroll
;             for (int i = 0; i < 8; ++i) { const int s = 8 * fr + i, grow = grow0 + i;
;                 if (s >= 1 && s <= 126 && grow < HALF_TOK) { u32x2 w; w.x = pk2(res[i][0], res[i][1]); w.y = pk2(res[i][2], res[i][3]); *(u32x2*)(G + (size_t)grow * DFF + cg0 + 4 * n) = w; } }
.Lupf_614:
	s_or_b64 exec, exec, s[68:69]
	v_mov_b32_e32 v203, v202
	v_mov_b32_e32 v201, v200
	v_mov_b32_e32 v199, v198
	global_load_dwordx4 v[70:73], v[206:207], off offset:16
	global_load_dwordx4 v[78:81], v[208:209], off offset:2064
	global_load_dwordx4 v[74:77], v[210:211], off offset:16
	global_load_dwordx4 v[82:85], v[204:205], off offset:16
	global_load_dwordx4 v[66:69], v[212:213], off offset:3088
	global_load_dwordx4 v[86:89], v[214:215], off offset:1040
	global_load_dwordx4 v[90:93], v[216:217], off offset:3088
	global_load_dwordx4 v[94:97], v[218:219], off offset:3088
	v_pk_mul_f32 v[98:99], v[46:47], v[202:203]
	v_pk_mul_f32 v[46:47], v[42:43], v[202:203]
	v_pk_mul_f32 v[102:103], v[58:59], v[200:201]
	v_pk_mul_f32 v[100:101], v[50:51], v[200:201]
	v_pk_mul_f32 v[108:109], v[62:63], v[198:199]
	v_pk_mul_f32 v[106:107], v[54:55], v[198:199]
	v_pk_mul_f32 v[48:49], v[48:49], v[202:203]
	v_pk_mul_f32 v[42:43], v[44:45], v[202:203]
	v_pk_mul_f32 v[54:55], v[52:53], v[200:201]
	v_pk_mul_f32 v[64:65], v[64:65], v[198:199]
	v_pk_mul_f32 v[104:105], v[56:57], v[198:199]
	v_mov_b32_dpp v112, v98 row_shr:1 row_mask:0xf bank_mask:0xf bound_ctrl:1
	v_mov_b32_dpp v110, v46 row_shr:1 row_mask:0xf bank_mask:0xf bound_ctrl:1
	v_mov_b32_dpp v113, v99 row_shr:1 row_mask:0xf bank_mask:0xf bound_ctrl:1
	v_mov_b32_dpp v111, v47 row_shr:1 row_mask:0xf bank_mask:0xf bound_ctrl:1
	v_mov_b32_dpp v58, v108 row_shl:1 row_mask:0xf bank_mask:0xf bound_ctrl:1
	v_mov_b32_dpp v50, v106 row_shl:1 row_mask:0xf bank_mask:0xf bound_ctrl:1
	v_mov_b32_dpp v59, v109 row_shl:1 row_mask:0xf bank_mask:0xf bound_ctrl:1
	v_mov_b32_dpp v51, v107 row_shl:1 row_mask:0xf bank_mask:0xf bound_ctrl:1
	v_mov_b32_dpp v114, v48 row_shr:1 row_mask:0xf bank_mask:0xf bound_ctrl:1
	v_mov_b32_dpp v62, v42 row_shr:1 row_mask:0xf bank_mask:0xf bound_ctrl:1
	v_mov_b32_dpp v115, v49 row_shr:1 row_mask:0xf bank_mask:0xf bound_ctrl:1
	v_mov_b32_dpp v63, v43 row_shr:1 row_mask:0xf bank_mask:0xf bound_ctrl:1
	v_pk_mul_f32 v[60:61], v[60:61], v[200:201]
	v_mov_b32_dpp v52, v64 row_shl:1 row_mask:0xf bank_mask:0xf bound_ctrl:1
	v_mov_b32_dpp v44, v104 row_shl:1 row_mask:0xf bank_mask:0xf bound_ctrl:1
	v_mov_b32_dpp v53, v65 row_shl:1 row_mask:0xf bank_mask:0xf bound_ctrl:1
	v_mov_b32_dpp v45, v105 row_shl:1 row_mask:0xf bank_mask:0xf bound_ctrl:1
	s_and_saveexec_b64 s[68:69], s[88:89]
	s_cbranch_execz .Lupf_616
	s_waitcnt vmcnt(7)
	v_pk_mul_f32 v[56:57], v[72:73], v[114:115]
	s_waitcnt vmcnt(6)
	v_pk_fma_f32 v[56:57], v[64:65], v[80:81], v[56:57]
	s_waitcnt vmcnt(5)
	v_pk_fma_f32 v[56:57], v[60:61], v[76:77], v[56:57]
	s_waitcnt vmcnt(3)
	v_pk_mul_f32 v[62:63], v[68:69], v[62:63]
	v_pk_add_f32 v[56:57], v[84:85], v[56:57]
	s_waitcnt vmcnt(2)
	v_pk_fma_f32 v[62:63], v[104:105], v[88:89], v[62:63]
	v_pk_mul_f32 v[114:115], v[56:57], v[56:57]
	v_fmamk_f32 v115, v115, 0xbdd2d3e8, v245
	v_fmamk_f32 v114, v114, 0xbdd2d3e8, v245
	v_mul_f32_e32 v115, v57, v115
	v_mul_f32_e32 v114, v56, v114
	v_pk_mul_f32 v[112:113], v[70:71], v[112:113]
	v_exp_f32_e32 v115, v115
	v_exp_f32_e32 v114, v114
	s_waitcnt vmcnt(1)
	v_pk_fma_f32 v[62:63], v[54:55], v[92:93], v[62:63]
	v_pk_fma_f32 v[112:113], v[108:109], v[78:79], v[112:113]
	v_pk_fma_f32 v[112:113], v[102:103], v[74:75], v[112:113]
	v_add_f32_e32 v115, 1.0, v115
	v_pk_add_f32 v[112:113], v[82:83], v[112:113]
	v_add_f32_e32 v114, 1.0, v114
	v_pk_mul_f32 v[116:117], v[112:113], v[112:113]
	v_rcp_f32_e32 v115, v115
	v_fmamk_f32 v117, v117, 0xbdd2d3e8, v245
	v_rcp_f32_e32 v114, v114
	v_mul_f32_e32 v117, v113, v117
	v_exp_f32_e32 v117, v117
	s_waitcnt vmcnt(0)
	v_pk_add_f32 v[62:63], v[96:97], v[62:63]
	v_pk_mul_f32 v[56:57], v[56:57], v[114:115]
	v_pk_fma_f32 v[110:111], v[66:67], v[110:111], v[94:95]
	v_pk_mul_f32 v[56:57], v[62:63], v[56:57]
	v_add_f32_e32 v62, 1.0, v117
	v_rcp_f32_e32 v63, v62
	v_fmamk_f32 v62, v116, 0xbdd2d3e8, v245
	v_mul_f32_e32 v62, v112, v62
	v_exp_f32_e32 v62, v62
	v_pk_fma_f32 v[110:111], v[106:107], v[86:87], v[110:111]
	v_add_f32_e32 v62, 1.0, v62
	v_rcp_f32_e32 v62, v62
	v_pk_fma_f32 v[110:111], v[100:101], v[90:91], v[110:111]
	v_pk_mul_f32 v[62:63], v[112:113], v[62:63]
	s_nop 0
	v_pk_mul_f32 v[62:63], v[110:111], v[62:63]
	s_nop 0
	v_cvt_pk_bf16_f32 v62, v62, v63
	v_cvt_pk_bf16_f32 v63, v56, v57
	v_mov_b64_e32 v[56:57], s[34:35]
	v_mad_i64_i32 v[56:57], s[70:71], v189, s85, v[56:57]
	v_lshl_add_u64 v[56:57], v[186:187], 1, v[56:57]
	global_store_dwordx2 v[56:57], v[62:63], off offset:8
;     __device__ __forceinline__ void operator()(const f32x4 (&acc)[2][2][4][2], const Unit& u, int wr, int wc, int fr, int fq) const {
;     ...
;                 for (int i = 0; i < 8; ++i) { xg[i] = acc[i >> 2][0][i & 3][n][j] * rs[i]; xv[i] = acc[i >> 2][1][i & 3][n][j] * rs[i]; }
;                 const float gp = __builtin_bit_cast(float, __builtin_amdgcn_update_dpp(0, __builtin_bit_cast(int, xg[7]), 0x111, 0xf, 0xf, false));
;                 const float gn = __builtin_bit_cast(float, __builtin_amdgcn_update_dpp(0, __builtin_bit_cast(int, xg[0]), 0x101, 0xf, 0xf, false));
;                 const float vp = __builtin_bit_cast(float, __builtin_amdgcn_update_dpp(0, __builtin_bit_cast(int, xv[7]), 0x111, 0xf, 0xf, false));
;                 const float vn = __builtin_bit_cast(float, __builtin_amdgcn_update_dpp(0, __builtin_bit_cast(int, xv[0]), 0x101, 0xf, 0xf, false));
; #pragma unroll
;                 for (int i = 0; i < 8; ++i) {
;                     float pg = i > 0 ? xg[i - 1] : gp, ng = i < 7 ? xg[i + 1] : gn, pv = i > 0 ? xv[i - 1] : vp, nv = i < 7 ? xv[i + 1] : vn;
;                     if (pz[i]) { pg = 0.f; pv = 0.f; } if (nz[i]) { ng = 0.f; nv = 0.f; }
;                     const float cgv = gw0 * pg + gw1 * xg[i] + gw2 * ng + gb;
;                     const float cvv = vw0 * pv + vw1 * xv[i] + vw2 * nv + vb;
;                     res[i][j] = gelu_tanh(cgv) * cvv;
;                 }
;             }
; #pragma unroll
;             for (int i = 0; i < 8; ++i) { const int s = 8 * fr + i, grow = grow0 + i;
;                 if (s >= 1 && s <= 126 && grow < HALF_TOK) { u32x2 w; w.x = pk2(res[i][0], res[i][1]); w.y = pk2(res[i][2], res[i][3]); *(u32x2*)(G + (size_t)grow * DFF + cg0 + 4 * n) = w; } }
.Lupf_616:
	s_or_b64 exec, exec, s[68:69]
	v_mov_b32_e32 v197, v196
	v_pk_mul_f32 v[62:63], v[38:39], v[196:197]
	v_pk_mul_f32 v[56:57], v[34:35], v[196:197]
	v_pk_mul_f32 v[38:39], v[40:41], v[196:197]
	v_pk_mul_f32 v[34:35], v[36:37], v[196:197]
	s_and_saveexec_b64 s[88:89], s[14:15]
	s_cbranch_execz .Lupf_618
	s_waitcnt vmcnt(6)
	v_pk_mul_f32 v[110:111], v[102:103], v[78:79]
	v_mov_b32_e32 v41, v107
	v_mov_b32_e32 v40, v106
	v_cndmask_b32_e64 v107, v63, 0, vcc
	v_cndmask_b32_e64 v106, v62, 0, vcc
	v_pk_fma_f32 v[36:37], v[108:109], v[70:71], v[110:111]
	v_cndmask_b32_e64 v109, v57, 0, vcc
	s_waitcnt vmcnt(5)
	v_pk_fma_f32 v[36:37], v[106:107], v[74:75], v[36:37]
	v_cndmask_b32_e64 v108, v56, 0, vcc
	s_waitcnt vmcnt(4)
	v_pk_add_f32 v[36:37], v[82:83], v[36:37]
	s_nop 0
	v_pk_mul_f32 v[106:107], v[36:37], v[36:37]
	s_nop 0
	v_fmamk_f32 v106, v106, 0xbdd2d3e8, v245
	v_mul_f32_e32 v106, v36, v106
	v_exp_f32_e32 v110, v106
	v_fmamk_f32 v106, v107, 0xbdd2d3e8, v245
	v_mul_f32_e32 v106, v37, v106
	v_exp_f32_e32 v111, v106
	v_add_f32_e32 v110, 1.0, v110
	v_rcp_f32_e32 v110, v110
	s_waitcnt vmcnt(2)
	v_pk_mul_f32 v[106:107], v[100:101], v[86:87]
	v_add_f32_e32 v111, 1.0, v111
	v_rcp_f32_e32 v111, v111
	v_pk_fma_f32 v[40:41], v[40:41], v[66:67], v[106:107]
	v_cndmask_b32_e64 v107, v35, 0, vcc
	s_waitcnt vmcnt(1)
	v_pk_fma_f32 v[40:41], v[108:109], v[90:91], v[40:41]
	v_pk_mul_f32 v[36:37], v[36:37], v[110:111]
	s_waitcnt vmcnt(0)
	v_pk_add_f32 v[40:41], v[94:95], v[40:41]
	v_pk_fma_f32 v[108:109], v[60:61], v[80:81], v[84:85]
	v_pk_mul_f32 v[36:37], v[40:41], v[36:37]
	v_mov_b32_e32 v41, v65
	v_mov_b32_e32 v40, v64
	v_mov_b32_e32 v65, v105
	v_mov_b32_e32 v64, v104
	v_cndmask_b32_e64 v105, v39, 0, vcc
	v_cndmask_b32_e64 v104, v38, 0, vcc
	v_pk_fma_f32 v[40:41], v[40:41], v[72:73], v[108:109]
	v_cndmask_b32_e64 v106, v34, 0, vcc
	v_pk_fma_f32 v[40:41], v[104:105], v[76:77], v[40:41]
	v_cvt_pk_bf16_f32 v36, v36, v37
	s_nop 0
	v_pk_mul_f32 v[104:105], v[40:41], v[40:41]
	s_nop 0
	v_fmamk_f32 v104, v104, 0xbdd2d3e8, v245
	v_mul_f32_e32 v104, v40, v104
	v_exp_f32_e32 v108, v104
	v_fmamk_f32 v104, v105, 0xbdd2d3e8, v245
	v_mul_f32_e32 v104, v41, v104
	v_exp_f32_e32 v109, v104
	v_add_f32_e32 v108, 1.0, v108
	v_rcp_f32_e32 v108, v108
	v_pk_fma_f32 v[104:105], v[54:55], v[88:89], v[96:97]
	v_add_f32_e32 v109, 1.0, v109
	v_rcp_f32_e32 v109, v109
	v_pk_fma_f32 v[64:65], v[64:65], v[68:69], v[104:105]
	v_pk_mul_f32 v[40:41], v[40:41], v[108:109]
	v_pk_fma_f32 v[64:65], v[106:107], v[92:93], v[64:65]
	s_nop 0
	s_nop 0
	v_pk_mul_f32 v[40:41], v[64:65], v[40:41]
	s_nop 0
	v_cvt_pk_bf16_f32 v37, v40, v41
	v_mov_b64_e32 v[40:41], s[34:35]
	v_mad_i64_i32 v[40:41], s[14:15], v191, s85, v[40:41]
	v_lshl_add_u64 v[40:41], v[186:187], 1, v[40:41]
	global_store_dwordx2 v[40:41], v[36:37], off offset:8
.Lupf_618:
	s_or_b64 exec, exec, s[88:89]
	v_mov_b32_e32 v195, v194
	v_pk_mul_f32 v[40:41], v[30:31], v[194:195]
	v_pk_mul_f32 v[36:37], v[26:27], v[194:195]
	v_pk_mul_f32 v[30:31], v[32:33], v[194:195]
	v_pk_mul_f32 v[26:27], v[28:29], v[194:195]
	s_and_saveexec_b64 s[14:15], s[16:17]
	s_cbranch_execz .Lupf_620
	v_cndmask_b32_e64 v29, v103, 0, vcc
	v_cndmask_b32_e64 v28, v102, 0, vcc
	s_waitcnt vmcnt(6)
	v_pk_mul_f32 v[102:103], v[62:63], v[78:79]
	v_pk_fma_f32 v[28:29], v[28:29], v[70:71], v[102:103]
	v_cndmask_b32_e64 v33, v101, 0, vcc
	s_waitcnt vmcnt(5)
	v_pk_fma_f32 v[28:29], v[40:41], v[74:75], v[28:29]
	v_cndmask_b32_e64 v32, v100, 0, vcc
	s_waitcnt vmcnt(4)
	v_pk_add_f32 v[28:29], v[82:83], v[28:29]
	v_pk_mul_f32 v[64:65], v[28:29], v[28:29]
	v_fmamk_f32 v64, v64, 0xbdd2d3e8, v245
	v_mul_f32_e32 v64, v28, v64
	v_exp_f32_e32 v102, v64
	v_fmamk_f32 v64, v65, 0xbdd2d3e8, v245
	v_mul_f32_e32 v64, v29, v64
	v_exp_f32_e32 v103, v64
	v_add_f32_e32 v102, 1.0, v102
	v_rcp_f32_e32 v102, v102
	s_waitcnt vmcnt(2)
	v_pk_mul_f32 v[64:65], v[56:57], v[86:87]
	v_add_f32_e32 v103, 1.0, v103
	v_rcp_f32_e32 v103, v103
	v_pk_fma_f32 v[32:33], v[32:33], v[66:67], v[64:65]
	v_cndmask_b32_e64 v55, v55, 0, vcc
	s_waitcnt vmcnt(1)
	v_pk_fma_f32 v[32:33], v[36:37], v[90:91], v[32:33]
	v_pk_mul_f32 v[28:29], v[28:29], v[102:103]
	s_waitcnt vmcnt(0)
	v_pk_add_f32 v[32:33], v[94:95], v[32:33]
	v_pk_fma_f32 v[100:101], v[38:39], v[80:81], v[84:85]
	v_pk_mul_f32 v[28:29], v[32:33], v[28:29]
	v_cndmask_b32_e64 v33, v61, 0, vcc
	v_cndmask_b32_e64 v32, v60, 0, vcc
	v_pk_fma_f32 v[32:33], v[32:33], v[72:73], v[100:101]
	v_cndmask_b32_e64 v54, v54, 0, vcc
	v_pk_fma_f32 v[32:33], v[30:31], v[76:77], v[32:33]
	v_pk_mul_f32 v[60:61], v[32:33], v[32:33]
	v_cvt_pk_bf16_f32 v28, v28, v29
	v_fmamk_f32 v60, v60, 0xbdd2d3e8, v245
	v_mul_f32_e32 v60, v32, v60
	v_exp_f32_e32 v100, v60
	v_fmamk_f32 v60, v61, 0xbdd2d3e8, v245
	v_mul_f32_e32 v60, v33, v60
	v_exp_f32_e32 v101, v60
	v_add_f32_e32 v100, 1.0, v100
	v_rcp_f32_e32 v100, v100
	v_pk_fma_f32 v[60:61], v[34:35], v[88:89], v[96:97]
	v_add_f32_e32 v101, 1.0, v101
	v_rcp_f32_e32 v101, v101
	v_pk_fma_f32 v[54:55], v[54:55], v[68:69], v[60:61]
	v_pk_mul_f32 v[32:33], v[32:33], v[100:101]
	v_pk_fma_f32 v[54:55], v[26:27], v[92:93], v[54:55]
	s_nop 0
	s_nop 0
	v_pk_mul_f32 v[32:33], v[54:55], v[32:33]
	s_nop 0
	v_cvt_pk_bf16_f32 v29, v32, v33
	v_mov_b64_e32 v[32:33], s[34:35]
	v_mad_i64_i32 v[32:33], s[16:17], v193, s85, v[32:33]
	v_lshl_add_u64 v[32:33], v[186:187], 1, v[32:33]
	global_store_dwordx2 v[32:33], v[28:29], off offset:8
;     __device__ __forceinline__ void operator()(const f32x4 (&acc)[2][2][4][2], const Unit& u, int wr, int wc, int fr, int fq) const {
;     ...
;                 for (int i = 0; i < 8; ++i) { xg[i] = acc[i >> 2][0][i & 3][n][j] * rs[i]; xv[i] = acc[i >> 2][1][i & 3][n][j] * rs[i]; }
;                 const float gp = __builtin_bit_cast(float, __builtin_amdgcn_update_dpp(0, __builtin_bit_cast(int, xg[7]), 0x111, 0xf, 0xf, false));
;                 const float gn = __builtin_bit_cast(float, __builtin_amdgcn_update_dpp(0, __builtin_bit_cast(int, xg[0]), 0x101, 0xf, 0xf, false));
;                 const float vp = __builtin_bit_cast(float, __builtin_amdgcn_update_dpp(0, __builtin_bit_cast(int, xv[7]), 0x111, 0xf, 0xf, false));
;                 const float vn = __builtin_bit_cast(float, __builtin_amdgcn_update_dpp(0, __builtin_bit_cast(int, xv[0]), 0x101, 0xf, 0xf, false));
; #pragma unroll
;                 for (int i = 0; i < 8; ++i) {
;                     float pg = i > 0 ? xg[i - 1] : gp, ng = i < 7 ? xg[i + 1] : gn, pv = i > 0 ? xv[i - 1] : vp, nv = i < 7 ? xv[i + 1] : vn;
;                     if (pz[i]) { pg = 0.f; pv = 0.f; } if (nz[i]) { ng = 0.f; nv = 0.f; }
;                     const float cgv = gw0 * pg + gw1 * xg[i] + gw2 * ng + gb;
;                     const float cvv = vw0 * pv + vw1 * xv[i] + vw2 * nv + vb;
;                     res[i][j] = gelu_tanh(cgv) * cvv;
;                 }
;             }
; #pragma unroll
;             for (int i = 0; i < 8; ++i) { const int s = 8 * fr + i, grow = grow0 + i;
;                 if (s >= 1 && s <= 126 && grow < HALF_TOK) { u32x2 w; w.x = pk2(res[i][0], res[i][1]); w.y = pk2(res[i][2], res[i][3]); *(u32x2*)(G + (size_t)grow * DFF + cg0 + 4 * n) = w; } }
.Lupf_620:
	s_or_b64 exec, exec, s[14:15]
	v_mov_b32_e32 v193, v192
	v_pk_mul_f32 v[32:33], v[22:23], v[192:193]
	v_pk_mul_f32 v[28:29], v[18:19], v[192:193]
	v_pk_mul_f32 v[22:23], v[24:25], v[192:193]
	v_pk_mul_f32 v[18:19], v[20:21], v[192:193]
	s_and_saveexec_b64 s[14:15], s[18:19]
	s_cbranch_execz .Lupf_622
	s_waitcnt vmcnt(6)
	v_pk_mul_f32 v[60:61], v[40:41], v[78:79]
	v_pk_fma_f32 v[20:21], v[62:63], v[70:71], v[60:61]
	s_waitcnt vmcnt(5)
	v_pk_fma_f32 v[20:21], v[32:33], v[74:75], v[20:21]
	s_waitcnt vmcnt(4)
	v_pk_add_f32 v[20:21], v[82:83], v[20:21]
	v_pk_mul_f32 v[54:55], v[20:21], v[20:21]
	v_fmamk_f32 v54, v54, 0xbdd2d3e8, v245
	v_mul_f32_e32 v54, v20, v54
	v_exp_f32_e32 v60, v54
	v_fmamk_f32 v54, v55, 0xbdd2d3e8, v245
	v_mul_f32_e32 v54, v21, v54
	v_exp_f32_e32 v61, v54
	v_add_f32_e32 v60, 1.0, v60
	v_rcp_f32_e32 v60, v60
	s_waitcnt vmcnt(2)
	v_pk_mul_f32 v[54:55], v[36:37], v[86:87]
	v_add_f32_e32 v61, 1.0, v61
	v_rcp_f32_e32 v61, v61
	v_pk_fma_f32 v[24:25], v[56:57], v[66:67], v[54:55]
	s_waitcnt vmcnt(1)
	v_pk_fma_f32 v[24:25], v[28:29], v[90:91], v[24:25]
	v_pk_mul_f32 v[20:21], v[20:21], v[60:61]
	s_waitcnt vmcnt(0)
	v_pk_add_f32 v[24:25], v[94:95], v[24:25]
	v_pk_fma_f32 v[56:57], v[30:31], v[80:81], v[84:85]
	v_pk_mul_f32 v[20:21], v[24:25], v[20:21]
	v_pk_fma_f32 v[24:25], v[38:39], v[72:73], v[56:57]
	v_pk_fma_f32 v[24:25], v[22:23], v[76:77], v[24:25]
	v_pk_mul_f32 v[38:39], v[24:25], v[24:25]
	v_cvt_pk_bf16_f32 v20, v20, v21
	v_fmamk_f32 v38, v38, 0xbdd2d3e8, v245
	v_mul_f32_e32 v38, v24, v38
	v_exp_f32_e32 v56, v38
	v_fmamk_f32 v38, v39, 0xbdd2d3e8, v245
	v_mul_f32_e32 v38, v25, v38
	v_exp_f32_e32 v57, v38
	v_add_f32_e32 v56, 1.0, v56
	v_rcp_f32_e32 v56, v56
	v_pk_fma_f32 v[38:39], v[26:27], v[88:89], v[96:97]
	v_add_f32_e32 v57, 1.0, v57
	v_rcp_f32_e32 v57, v57
	v_pk_fma_f32 v[34:35], v[34:35], v[68:69], v[38:39]
	v_pk_mul_f32 v[24:25], v[24:25], v[56:57]
	v_pk_fma_f32 v[34:35], v[18:19], v[92:93], v[34:35]
	s_nop 0
	s_nop 0
	v_pk_mul_f32 v[24:25], v[34:35], v[24:25]
	s_nop 0
	v_cvt_pk_bf16_f32 v21, v24, v25
	v_mov_b64_e32 v[24:25], s[34:35]
	v_mad_i64_i32 v[24:25], s[16:17], v150, s85, v[24:25]
	v_lshl_add_u64 v[24:25], v[186:187], 1, v[24:25]
	global_store_dwordx2 v[24:25], v[20:21], off offset:8
.Lupf_622:
	s_or_b64 exec, exec, s[14:15]
	v_mov_b32_e32 v191, v190
	v_pk_mul_f32 v[24:25], v[14:15], v[190:191]
	v_pk_mul_f32 v[20:21], v[10:11], v[190:191]
	v_pk_mul_f32 v[14:15], v[16:17], v[190:191]
	v_pk_mul_f32 v[10:11], v[12:13], v[190:191]
	s_and_saveexec_b64 s[14:15], s[20:21]
	s_cbranch_execz .Lupf_624
	s_waitcnt vmcnt(6)
	v_pk_mul_f32 v[38:39], v[32:33], v[78:79]
	v_pk_fma_f32 v[12:13], v[40:41], v[70:71], v[38:39]
	s_waitcnt vmcnt(5)
	v_pk_fma_f32 v[12:13], v[24:25], v[74:75], v[12:13]
	s_waitcnt vmcnt(4)
	v_pk_add_f32 v[12:13], v[82:83], v[12:13]
	v_pk_mul_f32 v[34:35], v[12:13], v[12:13]
	v_fmamk_f32 v34, v34, 0xbdd2d3e8, v245
	v_mul_f32_e32 v34, v12, v34
	v_exp_f32_e32 v38, v34
	v_fmamk_f32 v34, v35, 0xbdd2d3e8, v245
	v_mul_f32_e32 v34, v13, v34
	v_exp_f32_e32 v39, v34
	v_add_f32_e32 v38, 1.0, v38
	v_rcp_f32_e32 v38, v38
	s_waitcnt vmcnt(2)
	v_pk_mul_f32 v[34:35], v[28:29], v[86:87]
	v_add_f32_e32 v39, 1.0, v39
	v_rcp_f32_e32 v39, v39
	v_pk_fma_f32 v[16:17], v[36:37], v[66:67], v[34:35]
	s_waitcnt vmcnt(1)
	v_pk_fma_f32 v[16:17], v[20:21], v[90:91], v[16:17]
	v_pk_mul_f32 v[12:13], v[12:13], v[38:39]
	s_waitcnt vmcnt(0)
	v_pk_add_f32 v[16:17], v[94:95], v[16:17]
	v_pk_fma_f32 v[36:37], v[22:23], v[80:81], v[84:85]
	v_pk_mul_f32 v[12:13], v[16:17], v[12:13]
	v_pk_fma_f32 v[16:17], v[30:31], v[72:73], v[36:37]
	v_pk_fma_f32 v[16:17], v[14:15], v[76:77], v[16:17]
	v_pk_mul_f32 v[30:31], v[16:17], v[16:17]
	v_cvt_pk_bf16_f32 v12, v12, v13
	v_fmamk_f32 v30, v30, 0xbdd2d3e8, v245
	v_mul_f32_e32 v30, v16, v30
	v_exp_f32_e32 v36, v30
	v_fmamk_f32 v30, v31, 0xbdd2d3e8, v245
	v_mul_f32_e32 v30, v17, v30
	v_exp_f32_e32 v37, v30
	v_add_f32_e32 v36, 1.0, v36
	v_rcp_f32_e32 v36, v36
	v_pk_fma_f32 v[30:31], v[18:19], v[88:89], v[96:97]
	v_add_f32_e32 v37, 1.0, v37
	v_rcp_f32_e32 v37, v37
	v_pk_fma_f32 v[26:27], v[26:27], v[68:69], v[30:31]
	v_pk_mul_f32 v[16:17], v[16:17], v[36:37]
	v_pk_fma_f32 v[26:27], v[10:11], v[92:93], v[26:27]
	s_nop 0
	s_nop 0
	v_pk_mul_f32 v[16:17], v[26:27], v[16:17]
	s_nop 0
	v_cvt_pk_bf16_f32 v13, v16, v17
	v_mov_b64_e32 v[16:17], s[34:35]
	v_mad_i64_i32 v[16:17], s[10:11], v151, s85, v[16:17]
	v_lshl_add_u64 v[16:17], v[186:187], 1, v[16:17]
	global_store_dwordx2 v[16:17], v[12:13], off offset:8

;     __device__ __forceinline__ void operator()(const f32x4 (&acc)[2][2][4][2], const Unit& u, int wr, int wc, int fr, int fq) const {
;     ...
;                 for (int i = 0; i < 8; ++i) { xg[i] = acc[i >> 2][0][i & 3][n][j] * rs[i]; xv[i] = acc[i >> 2][1][i & 3][n][j] * rs[i]; }
;                 const float gp = __builtin_bit_cast(float, __builtin_amdgcn_update_dpp(0, __builtin_bit_cast(int, xg[7]), 0x111, 0xf, 0xf, false));
;                 const float gn = __builtin_bit_cast(float, __builtin_amdgcn_update_dpp(0, __builtin_bit_cast(int, xg[0]), 0x101, 0xf, 0xf, false));
;                 const float vp = __builtin_bit_cast(float, __builtin_amdgcn_update_dpp(0, __builtin_bit_cast(int, xv[7]), 0x111, 0xf, 0xf, false));
;                 const float vn = __builtin_bit_cast(float, __builtin_amdgcn_update_dpp(0, __builtin_bit_cast(int, xv[0]), 0x101, 0xf, 0xf, false));
; #pragma unroll
;                 for (int i = 0; i < 8; ++i) {
;                     float pg = i > 0 ? xg[i - 1] : gp, ng = i < 7 ? xg[i + 1] : gn, pv = i > 0 ? xv[i - 1] : vp, nv = i < 7 ? xv[i + 1] : vn;
;                     if (pz[i]) { pg = 0.f; pv = 0.f; } if (nz[i]) { ng = 0.f; nv = 0.f; }
;                     const float cgv = gw0 * pg + gw1 * xg[i] + gw2 * ng + gb;
;                     const float cvv = vw0 * pv + vw1 * xv[i] + vw2 * nv + vb;
;                     res[i][j] = gelu_tanh(cgv) * cvv;
;                 }
;             }
; #pragma unroll
;             for (int i = 0; i < 8; ++i) { const int s = 8 * fr + i, grow = grow0 + i;
;                 if (s >= 1 && s <= 126 && grow < HALF_TOK) { u32x2 w; w.x = pk2(res[i][0], res[i][1]); w.y = pk2(res[i][2], res[i][3]); *(u32x2*)(G + (size_t)grow * DFF + cg0 + 4 * n) = w; } }
.Lupf_627:
	s_waitcnt vmcnt(6)
	v_pk_mul_f32 v[8:9], v[98:99], v[78:79]
	v_pk_fma_f32 v[4:5], v[16:17], v[70:71], v[8:9]
	v_mov_b32_e32 v8, v12
	s_waitcnt vmcnt(5)
	v_pk_fma_f32 v[4:5], v[74:75], v[58:59], v[4:5]
	v_mov_b32_e32 v9, v13
	s_waitcnt vmcnt(4)
	v_pk_add_f32 v[4:5], v[82:83], v[4:5]
	v_pk_mul_f32 v[10:11], v[4:5], v[4:5]
	v_fmamk_f32 v10, v10, 0xbdd2d3e8, v245
	v_mul_f32_e32 v10, v4, v10
	v_exp_f32_e32 v12, v10
	v_fmamk_f32 v10, v11, 0xbdd2d3e8, v245
	v_mul_f32_e32 v10, v5, v10
	v_exp_f32_e32 v13, v10
	v_add_f32_e32 v12, 1.0, v12
	v_rcp_f32_e32 v12, v12
	s_waitcnt vmcnt(2)
	v_pk_mul_f32 v[10:11], v[46:47], v[86:87]
	v_add_f32_e32 v13, 1.0, v13
	v_rcp_f32_e32 v13, v13
	v_pk_fma_f32 v[8:9], v[8:9], v[66:67], v[10:11]
	s_waitcnt vmcnt(1)
	v_pk_fma_f32 v[8:9], v[90:91], v[50:51], v[8:9]
	v_pk_mul_f32 v[4:5], v[4:5], v[12:13]
	s_waitcnt vmcnt(0)
	v_pk_add_f32 v[8:9], v[94:95], v[8:9]
	s_nop 0
	v_pk_mul_f32 v[4:5], v[8:9], v[4:5]
	v_pk_fma_f32 v[8:9], v[48:49], v[80:81], v[84:85]
	v_cvt_pk_bf16_f32 v4, v4, v5
	v_pk_fma_f32 v[6:7], v[6:7], v[72:73], v[8:9]
	s_nop 0
	v_pk_fma_f32 v[6:7], v[76:77], v[52:53], v[6:7]
	s_nop 0
	s_nop 0
	v_pk_mul_f32 v[8:9], v[6:7], v[6:7]
	s_nop 0
	v_fmamk_f32 v8, v8, 0xbdd2d3e8, v245
	v_mul_f32_e32 v8, v6, v8
	v_exp_f32_e32 v10, v8
	v_fmamk_f32 v8, v9, 0xbdd2d3e8, v245
	v_mul_f32_e32 v8, v7, v8
	v_exp_f32_e32 v11, v8
	v_add_f32_e32 v10, 1.0, v10
	v_rcp_f32_e32 v10, v10
	v_pk_fma_f32 v[8:9], v[42:43], v[88:89], v[96:97]
	v_add_f32_e32 v11, 1.0, v11
	v_rcp_f32_e32 v11, v11
	v_pk_fma_f32 v[2:3], v[2:3], v[68:69], v[8:9]
	v_pk_mul_f32 v[6:7], v[6:7], v[10:11]
	v_pk_fma_f32 v[2:3], v[92:93], v[44:45], v[2:3]
	s_nop 0
	s_nop 0
	v_pk_mul_f32 v[2:3], v[2:3], v[6:7]
	s_nop 0
	v_cvt_pk_bf16_f32 v5, v2, v3
	v_mov_b64_e32 v[2:3], s[34:35]
	v_mad_i64_i32 v[2:3], s[12:13], v156, s85, v[2:3]
	v_lshl_add_u64 v[2:3], v[186:187], 1, v[2:3]
	global_store_dwordx2 v[2:3], v[4:5], off offset:8

;     __device__ __forceinline__ void operator()(const f32x4 (&acc)[2][2][4][2], const Unit& u, int wr, int wc, int fr, int fq) const {
;     ...
;                 for (int i = 0; i < 8; ++i) { xg[i] = acc[i >> 2][0][i & 3][n][j] * rs[i]; xv[i] = acc[i >> 2][1][i & 3][n][j] * rs[i]; }
;                 const float gp = __builtin_bit_cast(float, __builtin_amdgcn_update_dpp(0, __builtin_bit_cast(int, xg[7]), 0x111, 0xf, 0xf, false));
;                 const float gn = __builtin_bit_cast(float, __builtin_amdgcn_update_dpp(0, __builtin_bit_cast(int, xg[0]), 0x101, 0xf, 0xf, false));
;                 const float vp = __builtin_bit_cast(float, __builtin_amdgcn_update_dpp(0, __builtin_bit_cast(int, xv[7]), 0x111, 0xf, 0xf, false));
;                 const float vn = __builtin_bit_cast(float, __builtin_amdgcn_update_dpp(0, __builtin_bit_cast(int, xv[0]), 0x101, 0xf, 0xf, false));
; #pragma unroll
;                 for (int i = 0; i < 8; ++i) {
;                     float pg = i > 0 ? xg[i - 1] : gp, ng = i < 7 ? xg[i + 1] : gn, pv = i > 0 ? xv[i - 1] : vp, nv = i < 7 ? xv[i + 1] : vn;
;                     if (pz[i]) { pg = 0.f; pv = 0.f; } if (nz[i]) { ng = 0.f; nv = 0.f; }
;                     const float cgv = gw0 * pg + gw1 * xg[i] + gw2 * ng + gb;
;                     const float cvv = vw0 * pv + vw1 * xv[i] + vw2 * nv + vb;
;                     res[i][j] = gelu_tanh(cgv) * cvv;
;                 }
;             }
; #pragma unroll
;             for (int i = 0; i < 8; ++i) { const int s = 8 * fr + i, grow = grow0 + i;
;                 if (s >= 1 && s <= 126 && grow < HALF_TOK) { u32x2 w; w.x = pk2(res[i][0], res[i][1]); w.y = pk2(res[i][2], res[i][3]); *(u32x2*)(G + (size_t)grow * DFF + cg0 + 4 * n) = w; } }
.Lupf_631:
	s_waitcnt vmcnt(6)
	v_pk_mul_f32 v[30:31], v[24:25], v[78:79]
	v_pk_fma_f32 v[4:5], v[32:33], v[70:71], v[30:31]
	s_waitcnt vmcnt(5)
	v_pk_fma_f32 v[4:5], v[16:17], v[74:75], v[4:5]
	s_waitcnt vmcnt(4)
	v_pk_add_f32 v[4:5], v[82:83], v[4:5]
	s_waitcnt vmcnt(2)
	v_pk_mul_f32 v[30:31], v[20:21], v[86:87]
	v_pk_mul_f32 v[26:27], v[4:5], v[4:5]
	v_fmamk_f32 v26, v26, 0xbdd2d3e8, v245
	v_fmamk_f32 v27, v27, 0xbdd2d3e8, v245
	v_mul_f32_e32 v26, v4, v26
	v_mul_f32_e32 v27, v5, v27
	v_exp_f32_e32 v26, v26
	v_exp_f32_e32 v27, v27
	v_pk_fma_f32 v[8:9], v[28:29], v[66:67], v[30:31]
	v_add_f32_e32 v26, 1.0, v26
	v_add_f32_e32 v27, 1.0, v27
	v_rcp_f32_e32 v26, v26
	v_rcp_f32_e32 v27, v27
	s_waitcnt vmcnt(1)
	v_pk_fma_f32 v[8:9], v[12:13], v[90:91], v[8:9]
	v_pk_mul_f32 v[28:29], v[14:15], v[80:81]
	s_waitcnt vmcnt(0)
	v_pk_add_f32 v[8:9], v[94:95], v[8:9]
	v_pk_mul_f32 v[4:5], v[4:5], v[26:27]
	v_pk_mul_f32 v[4:5], v[8:9], v[4:5]
	v_pk_fma_f32 v[8:9], v[22:23], v[72:73], v[28:29]
	v_pk_fma_f32 v[8:9], v[6:7], v[76:77], v[8:9]
	v_pk_fma_f32 v[28:29], v[10:11], v[88:89], v[96:97]
	v_pk_add_f32 v[8:9], v[84:85], v[8:9]
	v_pk_mul_f32 v[22:23], v[8:9], v[8:9]
	v_fmamk_f32 v22, v22, 0xbdd2d3e8, v245
	v_fmamk_f32 v23, v23, 0xbdd2d3e8, v245
	v_mul_f32_e32 v22, v8, v22
	v_mul_f32_e32 v23, v9, v23
	v_exp_f32_e32 v22, v22
	v_exp_f32_e32 v23, v23
	v_pk_fma_f32 v[18:19], v[18:19], v[68:69], v[28:29]
	v_cvt_pk_bf16_f32 v4, v4, v5
	v_add_f32_e32 v22, 1.0, v22
	v_add_f32_e32 v23, 1.0, v23
	v_rcp_f32_e32 v22, v22
	v_rcp_f32_e32 v23, v23
	v_pk_fma_f32 v[18:19], v[2:3], v[92:93], v[18:19]
	v_pk_mul_f32 v[8:9], v[8:9], v[22:23]
	s_nop 0
	v_pk_mul_f32 v[8:9], v[18:19], v[8:9]
	s_nop 0
	v_cvt_pk_bf16_f32 v5, v8, v9
	v_mov_b64_e32 v[8:9], s[34:35]
	v_mad_i64_i32 v[8:9], s[14:15], v152, s85, v[8:9]
	v_lshl_add_u64 v[8:9], v[186:187], 1, v[8:9]
	global_store_dwordx2 v[8:9], v[4:5], off offset:8
	s_or_b64 exec, exec, s[10:11]
	s_and_saveexec_b64 s[10:11], s[24:25]
	s_cbranch_execz .Lupf_626
.Lupf_632:
	s_waitcnt vmcnt(6)
	v_pk_mul_f32 v[18:19], v[16:17], v[78:79]
	v_pk_fma_f32 v[4:5], v[24:25], v[70:71], v[18:19]
	s_waitcnt vmcnt(5)
	v_pk_fma_f32 v[4:5], v[98:99], v[74:75], v[4:5]
	s_waitcnt vmcnt(4)
	v_pk_add_f32 v[4:5], v[82:83], v[4:5]
	s_waitcnt vmcnt(2)
	v_pk_mul_f32 v[22:23], v[12:13], v[86:87]
	v_pk_mul_f32 v[8:9], v[4:5], v[4:5]
	v_fmamk_f32 v8, v8, 0xbdd2d3e8, v245
	v_fmamk_f32 v9, v9, 0xbdd2d3e8, v245
	v_mul_f32_e32 v8, v4, v8
	v_mul_f32_e32 v9, v5, v9
	v_exp_f32_e32 v8, v8
	v_exp_f32_e32 v9, v9
	v_pk_fma_f32 v[18:19], v[20:21], v[66:67], v[22:23]
	v_add_f32_e32 v8, 1.0, v8
	v_add_f32_e32 v9, 1.0, v9
	v_rcp_f32_e32 v8, v8
	v_rcp_f32_e32 v9, v9
	s_waitcnt vmcnt(1)
	v_pk_fma_f32 v[18:19], v[46:47], v[90:91], v[18:19]
	v_pk_mul_f32 v[20:21], v[6:7], v[80:81]
	s_waitcnt vmcnt(0)
	v_pk_add_f32 v[18:19], v[94:95], v[18:19]
	v_pk_mul_f32 v[4:5], v[4:5], v[8:9]
	v_pk_fma_f32 v[8:9], v[14:15], v[72:73], v[20:21]
	v_pk_fma_f32 v[8:9], v[48:49], v[76:77], v[8:9]
	v_pk_add_f32 v[8:9], v[84:85], v[8:9]
	v_pk_fma_f32 v[20:21], v[2:3], v[88:89], v[96:97]
	v_pk_mul_f32 v[14:15], v[8:9], v[8:9]
	v_pk_mul_f32 v[4:5], v[18:19], v[4:5]
	v_fmamk_f32 v14, v14, 0xbdd2d3e8, v245
	v_fmamk_f32 v15, v15, 0xbdd2d3e8, v245
	v_mul_f32_e32 v14, v8, v14
	v_mul_f32_e32 v15, v9, v15
	v_exp_f32_e32 v14, v14
	v_exp_f32_e32 v15, v15
	v_add_f32_e32 v14, 1.0, v14
	v_add_f32_e32 v15, 1.0, v15
	v_rcp_f32_e32 v14, v14
	v_rcp_f32_e32 v15, v15
	v_pk_fma_f32 v[10:11], v[10:11], v[68:69], v[20:21]
	v_cvt_pk_bf16_f32 v4, v4, v5
	v_pk_fma_f32 v[10:11], v[42:43], v[92:93], v[10:11]
	v_pk_mul_f32 v[8:9], v[8:9], v[14:15]
	s_nop 0
	v_pk_mul_f32 v[8:9], v[10:11], v[8:9]
	s_nop 0
	v_cvt_pk_bf16_f32 v5, v8, v9
	v_mov_b64_e32 v[8:9], s[34:35]
	v_mad_i64_i32 v[8:9], s[12:13], v153, s85, v[8:9]
	v_lshl_add_u64 v[8:9], v[186:187], 1, v[8:9]
	global_store_dwordx2 v[8:9], v[4:5], off offset:8
	s_or_b64 exec, exec, s[10:11]
	s_and_saveexec_b64 s[10:11], s[28:29]
	s_cbranch_execnz .Lupf_627
	s_branch .Lupf_628
